# v41 + redundant post-barrier s_waitcnt lgkmcnt(0) removed in the GEMM K-loops (the inline-asm lgkmcnt(0) before the barrier already covers it)
# baseline (speedup 1.0000x reference)
; #define PG8_STAGE(bufoff, gbase, voff) do { _Pragma("unroll") for (int _i = 0; _i < 2; ++_i) \
;         __builtin_amdgcn_global_load_lds((const unsigned*)((const char*)(gbase) + (voff)[_i]), (PG8_LAS unsigned*)(lds + (bufoff) + ldsw + _i * 8192), 16, 0, 0); } while (0)
; #define PG8_WAIT_V(n) asm volatile("s_waitcnt vmcnt(" #n ")" ::: "memory")
; #define PG8_WAIT_L(n) asm volatile("s_waitcnt lgkmcnt(" #n ")" ::: "memory")
; #define PG8_BAR __builtin_amdgcn_s_barrier()
; #define PG8_SCHED __builtin_amdgcn_sched_barrier(0)
;     ...
;             PG8_LDB(B0, 0, 0); PG8_LDB(B1, 0, 1); PG8_SCHED; PG8_LDA(At, 0, 0); PG8_STAGE(PG8_SA(1, 1), a1 + hstep, voffA);
;             PG8_WAIT_V(8); PG8_WAIT_L(0); PG8_BAR; PG8_MMA(0, 0, At, B0); PG8_MMA(0, 1, At, B1); PG8_BAR; PG8_SCHED;
;             PG8_LDA(At, 0, 1); PG8_STAGE(PG8_SB(0, 0), b2, voffB); PG8_STAGE(PG8_SB(0, 1), b2 + hstep, voffB); PG8_STAGE(PG8_SA(0, 0), a2, voffA);
.LBB0_248:
	v_add_u32_e32 v155, s68, v149
	ds_read_b128 v[166:169], v155
	ds_read_b128 v[170:173], v155 offset:1024
	ds_read_b128 v[174:177], v155 offset:2048
	ds_read_b128 v[178:181], v155 offset:3072
	v_add_u32_e32 v155, s69, v149
	ds_read_b128 v[182:185], v155
	ds_read_b128 v[186:189], v155 offset:1024
	ds_read_b128 v[190:193], v155 offset:2048
	ds_read_b128 v[194:197], v155 offset:3072
	s_add_u32 s33, s50, 0xfffc0080
	s_addc_u32 s54, s51, -1
	s_and_b64 s[52:53], s[52:53], exec
	s_cselect_b32 s55, s25, s54
	s_cselect_b32 s54, s34, s33
	s_cselect_b32 s53, s21, s73
	s_cselect_b32 s52, s35, s72
	v_lshl_add_u64 v[210:211], s[50:51], 0, v[138:139]
	s_add_i32 m0, s59, 0xc000
	ds_read_b128 v[198:201], v153
	ds_read_b128 v[202:205], v153 offset:1024
	ds_read_b128 v[206:209], v153 offset:2048
	ds_read_b128 v[214:217], v153 offset:3072
	ds_read_b128 v[218:221], v153 offset:4096
	ds_read_b128 v[222:225], v153 offset:5120
	ds_read_b128 v[226:229], v153 offset:6144
	ds_read_b128 v[230:233], v153 offset:7168
	global_load_lds_dwordx4 v[210:211], off
	v_lshl_add_u64 v[210:211], s[50:51], 0, v[140:141]
	s_add_i32 m0, s59, 0xe000
	s_nop 0
	global_load_lds_dwordx4 v[210:211], off
	s_waitcnt vmcnt(8)
	s_waitcnt lgkmcnt(0)
	s_barrier
	v_mfma_i32_16x16x64_i8 v[124:127], v[166:169], v[198:201], v[124:127]
	v_mfma_i32_16x16x64_i8 v[124:127], v[170:173], v[202:205], v[124:127]
	v_mfma_i32_16x16x64_i8 v[116:119], v[174:177], v[198:201], v[116:119]
	v_mfma_i32_16x16x64_i8 v[116:119], v[178:181], v[202:205], v[116:119]
	v_mfma_i32_16x16x64_i8 v[108:111], v[166:169], v[206:209], v[108:111]
	v_mfma_i32_16x16x64_i8 v[108:111], v[170:173], v[214:217], v[108:111]
	v_mfma_i32_16x16x64_i8 v[100:103], v[174:177], v[206:209], v[100:103]
	v_mfma_i32_16x16x64_i8 v[100:103], v[178:181], v[214:217], v[100:103]
	v_mfma_i32_16x16x64_i8 v[92:95], v[166:169], v[218:221], v[92:95]
	v_mfma_i32_16x16x64_i8 v[92:95], v[170:173], v[222:225], v[92:95]
	v_mfma_i32_16x16x64_i8 v[84:87], v[174:177], v[218:221], v[84:87]
	v_mfma_i32_16x16x64_i8 v[84:87], v[178:181], v[222:225], v[84:87]
	v_mfma_i32_16x16x64_i8 v[76:79], v[166:169], v[226:229], v[76:79]
	v_mfma_i32_16x16x64_i8 v[76:79], v[170:173], v[230:233], v[76:79]
	v_mfma_i32_16x16x64_i8 v[68:71], v[174:177], v[226:229], v[68:71]
	v_mfma_i32_16x16x64_i8 v[68:71], v[178:181], v[230:233], v[68:71]
	v_mfma_i32_16x16x64_i8 v[120:123], v[182:185], v[198:201], v[120:123]
	v_mfma_i32_16x16x64_i8 v[120:123], v[186:189], v[202:205], v[120:123]
	v_mfma_i32_16x16x64_i8 v[112:115], v[190:193], v[198:201], v[112:115]
	v_mfma_i32_16x16x64_i8 v[112:115], v[194:197], v[202:205], v[112:115]
	v_mfma_i32_16x16x64_i8 v[104:107], v[182:185], v[206:209], v[104:107]
	v_mfma_i32_16x16x64_i8 v[104:107], v[186:189], v[214:217], v[104:107]
	v_mfma_i32_16x16x64_i8 v[96:99], v[190:193], v[206:209], v[96:99]
	v_mfma_i32_16x16x64_i8 v[96:99], v[194:197], v[214:217], v[96:99]
	v_mfma_i32_16x16x64_i8 v[88:91], v[182:185], v[218:221], v[88:91]
	v_mfma_i32_16x16x64_i8 v[88:91], v[186:189], v[222:225], v[88:91]
	v_mfma_i32_16x16x64_i8 v[80:83], v[190:193], v[218:221], v[80:83]
	v_mfma_i32_16x16x64_i8 v[80:83], v[194:197], v[222:225], v[80:83]
	v_mfma_i32_16x16x64_i8 v[72:75], v[182:185], v[226:229], v[72:75]
	v_mfma_i32_16x16x64_i8 v[72:75], v[186:189], v[230:233], v[72:75]
	v_mfma_i32_16x16x64_i8 v[64:67], v[190:193], v[226:229], v[64:67]
	v_mfma_i32_16x16x64_i8 v[64:67], v[194:197], v[230:233], v[64:67]
	s_barrier
	s_add_i32 s33, s68, s56
	v_lshl_add_u64 v[210:211], s[52:53], 0, v[132:133]
	s_mov_b32 m0, s33
	ds_read_b128 v[198:201], v153 offset:16384
	ds_read_b128 v[202:205], v153 offset:17408
	ds_read_b128 v[206:209], v153 offset:18432
	ds_read_b128 v[214:217], v153 offset:19456
	ds_read_b128 v[218:221], v153 offset:20480
	ds_read_b128 v[222:225], v153 offset:21504
	ds_read_b128 v[226:229], v153 offset:22528
	ds_read_b128 v[230:233], v153 offset:23552
	global_load_lds_dwordx4 v[210:211], off
	s_add_i32 m0, s33, 0x2000
	s_add_u32 s76, s52, 0x40000
	v_lshl_add_u64 v[234:235], s[52:53], 0, v[128:129]
	s_addc_u32 s77, s53, 0
	s_add_i32 s33, s69, s56
	global_load_lds_dwordx4 v[234:235], off
	v_lshl_add_u64 v[236:237], s[76:77], 0, v[132:133]
	s_mov_b32 m0, s33
	v_lshl_add_u64 v[238:239], s[54:55], 0, v[130:131]
	global_load_lds_dwordx4 v[236:237], off
	v_lshl_add_u64 v[236:237], s[76:77], 0, v[128:129]
	s_add_i32 m0, s33, 0x2000
	s_nop 0
	global_load_lds_dwordx4 v[236:237], off
	v_lshl_add_u64 v[236:237], s[54:55], 0, v[134:135]
	s_mov_b32 m0, s59
	s_nop 0
	global_load_lds_dwordx4 v[236:237], off
	s_mov_b32 m0, s60
	s_nop 0
	global_load_lds_dwordx4 v[238:239], off
	s_waitcnt vmcnt(8)
	s_waitcnt lgkmcnt(0)
	s_barrier
; #define PG8_STAGE(bufoff, gbase, voff) do { _Pragma("unroll") for (int _i = 0; _i < 2; ++_i) \
;         __builtin_amdgcn_global_load_lds((const unsigned*)((const char*)(gbase) + (voff)[_i]), (PG8_LAS unsigned*)(lds + (bufoff) + ldsw + _i * 8192), 16, 0, 0); } while (0)
; #define PG8_WAIT_V(n) asm volatile("s_waitcnt vmcnt(" #n ")" ::: "memory")
; #define PG8_WAIT_L(n) asm volatile("s_waitcnt lgkmcnt(" #n ")" ::: "memory")
; #define PG8_BAR __builtin_amdgcn_s_barrier()
; #define PG8_SCHED __builtin_amdgcn_sched_barrier(0)
;     ...
;             PG8_WAIT_V(8); PG8_WAIT_L(0); PG8_BAR; PG8_MMA(1, 0, At, B0); PG8_MMA(1, 1, At, B1); PG8_BAR; PG8_SCHED;
;             PG8_LDB(B0, 1, 0); PG8_LDB(B1, 1, 1); PG8_SCHED; PG8_LDA(At, 1, 0); PG8_STAGE(PG8_SA(0, 1), a2 + hstep, voffA);
;             PG8_WAIT_V(8); PG8_WAIT_L(0); PG8_BAR; PG8_MMA(0, 0, At, B0); PG8_MMA(0, 1, At, B1); PG8_BAR; PG8_SCHED;
	v_mfma_i32_16x16x64_i8 v[60:63], v[166:169], v[198:201], v[60:63]
	v_mfma_i32_16x16x64_i8 v[60:63], v[170:173], v[202:205], v[60:63]
	v_mfma_i32_16x16x64_i8 v[52:55], v[174:177], v[198:201], v[52:55]
	v_mfma_i32_16x16x64_i8 v[52:55], v[178:181], v[202:205], v[52:55]
	v_mfma_i32_16x16x64_i8 v[44:47], v[166:169], v[206:209], v[44:47]
	v_mfma_i32_16x16x64_i8 v[44:47], v[170:173], v[214:217], v[44:47]
	v_mfma_i32_16x16x64_i8 v[36:39], v[174:177], v[206:209], v[36:39]
	v_mfma_i32_16x16x64_i8 v[36:39], v[178:181], v[214:217], v[36:39]
	v_mfma_i32_16x16x64_i8 v[28:31], v[166:169], v[218:221], v[28:31]
	v_mfma_i32_16x16x64_i8 v[28:31], v[170:173], v[222:225], v[28:31]
	v_mfma_i32_16x16x64_i8 v[20:23], v[174:177], v[218:221], v[20:23]
	v_mfma_i32_16x16x64_i8 v[20:23], v[178:181], v[222:225], v[20:23]
	v_mfma_i32_16x16x64_i8 v[12:15], v[166:169], v[226:229], v[12:15]
	v_mfma_i32_16x16x64_i8 v[12:15], v[170:173], v[230:233], v[12:15]
	v_mfma_i32_16x16x64_i8 v[4:7], v[174:177], v[226:229], v[4:7]
	v_mfma_i32_16x16x64_i8 v[4:7], v[178:181], v[230:233], v[4:7]
	v_mfma_i32_16x16x64_i8 v[56:59], v[182:185], v[198:201], v[56:59]
	v_mfma_i32_16x16x64_i8 v[56:59], v[186:189], v[202:205], v[56:59]
	v_mfma_i32_16x16x64_i8 v[48:51], v[190:193], v[198:201], v[48:51]
	v_mfma_i32_16x16x64_i8 v[48:51], v[194:197], v[202:205], v[48:51]
	v_mfma_i32_16x16x64_i8 v[40:43], v[182:185], v[206:209], v[40:43]
	v_mfma_i32_16x16x64_i8 v[40:43], v[186:189], v[214:217], v[40:43]
	v_mfma_i32_16x16x64_i8 v[32:35], v[190:193], v[206:209], v[32:35]
	v_mfma_i32_16x16x64_i8 v[32:35], v[194:197], v[214:217], v[32:35]
	v_mfma_i32_16x16x64_i8 v[24:27], v[182:185], v[218:221], v[24:27]
	v_mfma_i32_16x16x64_i8 v[24:27], v[186:189], v[222:225], v[24:27]
	v_mfma_i32_16x16x64_i8 v[16:19], v[190:193], v[218:221], v[16:19]
	v_mfma_i32_16x16x64_i8 v[16:19], v[194:197], v[222:225], v[16:19]
	v_mfma_i32_16x16x64_i8 v[8:11], v[182:185], v[226:229], v[8:11]
	v_mfma_i32_16x16x64_i8 v[8:11], v[186:189], v[230:233], v[8:11]
	v_mfma_i32_16x16x64_i8 v[0:3], v[190:193], v[226:229], v[0:3]
	v_mfma_i32_16x16x64_i8 v[0:3], v[194:197], v[230:233], v[0:3]
	s_barrier
	s_add_i32 s33, 0, 0x18000
	v_add_u32_e32 v155, s33, v149
	s_add_i32 s75, 0, 0x1c000
	ds_read_b128 v[166:169], v155
	ds_read_b128 v[170:173], v155 offset:1024
	ds_read_b128 v[174:177], v155 offset:2048
	ds_read_b128 v[178:181], v155 offset:3072
	v_add_u32_e32 v155, s75, v149
	ds_read_b128 v[182:185], v155
	ds_read_b128 v[186:189], v155 offset:1024
	ds_read_b128 v[190:193], v155 offset:2048
	ds_read_b128 v[194:197], v155 offset:3072
	s_add_u32 s54, s54, 0x40000
	s_addc_u32 s55, s55, 0
	s_mov_b32 m0, s61
	v_lshl_add_u64 v[240:241], s[54:55], 0, v[134:135]
	ds_read_b128 v[198:201], v153 offset:32768
	ds_read_b128 v[202:205], v153 offset:33792
	ds_read_b128 v[206:209], v153 offset:34816
	ds_read_b128 v[214:217], v153 offset:35840
	ds_read_b128 v[218:221], v153 offset:36864
	ds_read_b128 v[222:225], v153 offset:37888
	ds_read_b128 v[226:229], v153 offset:38912
	ds_read_b128 v[230:233], v153 offset:39936
	global_load_lds_dwordx4 v[240:241], off
	v_lshl_add_u64 v[240:241], s[54:55], 0, v[130:131]
	s_mov_b32 m0, s62
	s_nop 0
	global_load_lds_dwordx4 v[240:241], off
	s_waitcnt vmcnt(8)
	s_waitcnt lgkmcnt(0)
	s_barrier
	v_mfma_i32_16x16x64_i8 v[124:127], v[166:169], v[198:201], v[124:127]
	v_mfma_i32_16x16x64_i8 v[124:127], v[170:173], v[202:205], v[124:127]
	v_mfma_i32_16x16x64_i8 v[116:119], v[174:177], v[198:201], v[116:119]
	v_mfma_i32_16x16x64_i8 v[116:119], v[178:181], v[202:205], v[116:119]
	v_mfma_i32_16x16x64_i8 v[108:111], v[166:169], v[206:209], v[108:111]
	v_mfma_i32_16x16x64_i8 v[108:111], v[170:173], v[214:217], v[108:111]
	v_mfma_i32_16x16x64_i8 v[100:103], v[174:177], v[206:209], v[100:103]
	v_mfma_i32_16x16x64_i8 v[100:103], v[178:181], v[214:217], v[100:103]
	v_mfma_i32_16x16x64_i8 v[92:95], v[166:169], v[218:221], v[92:95]
	v_mfma_i32_16x16x64_i8 v[92:95], v[170:173], v[222:225], v[92:95]
	v_mfma_i32_16x16x64_i8 v[84:87], v[174:177], v[218:221], v[84:87]
	v_mfma_i32_16x16x64_i8 v[84:87], v[178:181], v[222:225], v[84:87]
	v_mfma_i32_16x16x64_i8 v[76:79], v[166:169], v[226:229], v[76:79]
	v_mfma_i32_16x16x64_i8 v[76:79], v[170:173], v[230:233], v[76:79]
	v_mfma_i32_16x16x64_i8 v[68:71], v[174:177], v[226:229], v[68:71]
	v_mfma_i32_16x16x64_i8 v[68:71], v[178:181], v[230:233], v[68:71]
	v_mfma_i32_16x16x64_i8 v[120:123], v[182:185], v[198:201], v[120:123]
	v_mfma_i32_16x16x64_i8 v[120:123], v[186:189], v[202:205], v[120:123]
	v_mfma_i32_16x16x64_i8 v[112:115], v[190:193], v[198:201], v[112:115]
	v_mfma_i32_16x16x64_i8 v[112:115], v[194:197], v[202:205], v[112:115]
	v_mfma_i32_16x16x64_i8 v[104:107], v[182:185], v[206:209], v[104:107]
	v_mfma_i32_16x16x64_i8 v[104:107], v[186:189], v[214:217], v[104:107]
	v_mfma_i32_16x16x64_i8 v[96:99], v[190:193], v[206:209], v[96:99]
	v_mfma_i32_16x16x64_i8 v[96:99], v[194:197], v[214:217], v[96:99]
	v_mfma_i32_16x16x64_i8 v[88:91], v[182:185], v[218:221], v[88:91]
	v_mfma_i32_16x16x64_i8 v[88:91], v[186:189], v[222:225], v[88:91]
	v_mfma_i32_16x16x64_i8 v[80:83], v[190:193], v[218:221], v[80:83]
	v_mfma_i32_16x16x64_i8 v[80:83], v[194:197], v[222:225], v[80:83]
	v_mfma_i32_16x16x64_i8 v[72:75], v[182:185], v[226:229], v[72:75]
	v_mfma_i32_16x16x64_i8 v[72:75], v[186:189], v[230:233], v[72:75]
	v_mfma_i32_16x16x64_i8 v[64:67], v[190:193], v[226:229], v[64:67]
	v_mfma_i32_16x16x64_i8 v[64:67], v[194:197], v[230:233], v[64:67]
	s_barrier
; #define PG8_STAGE(bufoff, gbase, voff) do { _Pragma("unroll") for (int _i = 0; _i < 2; ++_i) \
;         __builtin_amdgcn_global_load_lds((const unsigned*)((const char*)(gbase) + (voff)[_i]), (PG8_LAS unsigned*)(lds + (bufoff) + ldsw + _i * 8192), 16, 0, 0); } while (0)
; #define PG8_WAIT_V(n) asm volatile("s_waitcnt vmcnt(" #n ")" ::: "memory")
; #define PG8_WAIT_L(n) asm volatile("s_waitcnt lgkmcnt(" #n ")" ::: "memory")
; #define PG8_BAR __builtin_amdgcn_s_barrier()
; #define PG8_SCHED __builtin_amdgcn_sched_barrier(0)
;     ...
;         for (int t = 0; t < nt; t += 2) {
;     ...
;             PG8_LDA(At, 1, 1); PG8_STAGE(PG8_SB(1, 0), b3, voffB); PG8_STAGE(PG8_SB(1, 1), b3 + hstep, voffB); PG8_STAGE(PG8_SA(1, 0), a3, voffA);
;             PG8_WAIT_V(8); PG8_WAIT_L(0); PG8_BAR; PG8_MMA(1, 0, At, B0); PG8_MMA(1, 1, At, B1); PG8_BAR; PG8_SCHED;
	s_add_i32 s33, s33, s56
	v_lshl_add_u64 v[210:211], v[210:211], 0, s[10:11]
	s_mov_b32 m0, s33
	ds_read_b128 v[198:201], v153 offset:49152
	ds_read_b128 v[202:205], v153 offset:50176
	ds_read_b128 v[206:209], v153 offset:51200
	ds_read_b128 v[214:217], v153 offset:52224
	ds_read_b128 v[218:221], v153 offset:53248
	ds_read_b128 v[222:225], v153 offset:54272
	ds_read_b128 v[226:229], v153 offset:55296
	ds_read_b128 v[230:233], v153 offset:56320
	global_load_lds_dwordx4 v[210:211], off
	s_add_i32 m0, s33, 0x2000
	s_add_u32 s52, s52, 0x40080
	v_lshl_add_u64 v[210:211], v[234:235], 0, s[10:11]
	s_addc_u32 s53, s53, 0
	s_add_i32 s33, s75, s56
	global_load_lds_dwordx4 v[210:211], off
	v_lshl_add_u64 v[210:211], s[52:53], 0, v[132:133]
	s_mov_b32 m0, s33
	s_nop 0
	global_load_lds_dwordx4 v[210:211], off
	v_lshl_add_u64 v[210:211], s[52:53], 0, v[128:129]
	s_add_i32 m0, s33, 0x2000
	s_nop 0
	global_load_lds_dwordx4 v[210:211], off
	v_lshl_add_u64 v[210:211], v[236:237], 0, s[10:11]
	s_mov_b32 m0, s64
	s_nop 0
	global_load_lds_dwordx4 v[210:211], off
	v_lshl_add_u64 v[210:211], v[238:239], 0, s[10:11]
	s_mov_b32 m0, s65
	s_nop 0
	global_load_lds_dwordx4 v[210:211], off
	s_waitcnt vmcnt(8)
	s_waitcnt lgkmcnt(0)
	s_barrier
	v_mfma_i32_16x16x64_i8 v[60:63], v[166:169], v[198:201], v[60:63]
	v_mfma_i32_16x16x64_i8 v[60:63], v[170:173], v[202:205], v[60:63]
	v_mfma_i32_16x16x64_i8 v[52:55], v[174:177], v[198:201], v[52:55]
	v_mfma_i32_16x16x64_i8 v[52:55], v[178:181], v[202:205], v[52:55]
	v_mfma_i32_16x16x64_i8 v[44:47], v[166:169], v[206:209], v[44:47]
	v_mfma_i32_16x16x64_i8 v[44:47], v[170:173], v[214:217], v[44:47]
	v_mfma_i32_16x16x64_i8 v[36:39], v[174:177], v[206:209], v[36:39]
	v_mfma_i32_16x16x64_i8 v[36:39], v[178:181], v[214:217], v[36:39]
	v_mfma_i32_16x16x64_i8 v[28:31], v[166:169], v[218:221], v[28:31]
	v_mfma_i32_16x16x64_i8 v[28:31], v[170:173], v[222:225], v[28:31]
	v_mfma_i32_16x16x64_i8 v[20:23], v[174:177], v[218:221], v[20:23]
	v_mfma_i32_16x16x64_i8 v[20:23], v[178:181], v[222:225], v[20:23]
	v_mfma_i32_16x16x64_i8 v[12:15], v[166:169], v[226:229], v[12:15]
	v_mfma_i32_16x16x64_i8 v[12:15], v[170:173], v[230:233], v[12:15]
	v_mfma_i32_16x16x64_i8 v[4:7], v[174:177], v[226:229], v[4:7]
	v_mfma_i32_16x16x64_i8 v[4:7], v[178:181], v[230:233], v[4:7]
	v_mfma_i32_16x16x64_i8 v[56:59], v[182:185], v[198:201], v[56:59]
	v_mfma_i32_16x16x64_i8 v[56:59], v[186:189], v[202:205], v[56:59]
	v_mfma_i32_16x16x64_i8 v[48:51], v[190:193], v[198:201], v[48:51]
	v_mfma_i32_16x16x64_i8 v[48:51], v[194:197], v[202:205], v[48:51]
	v_mfma_i32_16x16x64_i8 v[40:43], v[182:185], v[206:209], v[40:43]
	v_mfma_i32_16x16x64_i8 v[40:43], v[186:189], v[214:217], v[40:43]
	v_mfma_i32_16x16x64_i8 v[32:35], v[190:193], v[206:209], v[32:35]
	v_mfma_i32_16x16x64_i8 v[32:35], v[194:197], v[214:217], v[32:35]
	v_mfma_i32_16x16x64_i8 v[24:27], v[182:185], v[218:221], v[24:27]
	v_mfma_i32_16x16x64_i8 v[24:27], v[186:189], v[222:225], v[24:27]
	v_mfma_i32_16x16x64_i8 v[16:19], v[190:193], v[218:221], v[16:19]
	v_mfma_i32_16x16x64_i8 v[16:19], v[194:197], v[222:225], v[16:19]
	v_mfma_i32_16x16x64_i8 v[8:11], v[182:185], v[226:229], v[8:11]
	v_mfma_i32_16x16x64_i8 v[8:11], v[186:189], v[230:233], v[8:11]
	v_mfma_i32_16x16x64_i8 v[0:3], v[190:193], v[226:229], v[0:3]
	v_mfma_i32_16x16x64_i8 v[0:3], v[194:197], v[230:233], v[0:3]
	s_barrier
	s_add_i32 s74, s74, 2
	s_add_u32 s50, s50, 0x100
	s_addc_u32 s51, s51, 0
	s_add_u32 s72, s72, 0x100
	s_addc_u32 s73, s73, 0
	s_cmp_gt_u32 s74, 13
	s_cbranch_scc1 .LBB0_251

; #define PG8_STAGE(bufoff, gbase, voff) do { _Pragma("unroll") for (int _i = 0; _i < 2; ++_i) \
;         __builtin_amdgcn_global_load_lds((const unsigned*)((const char*)(gbase) + (voff)[_i]), (PG8_LAS unsigned*)(lds + (bufoff) + ldsw + _i * 8192), 16, 0, 0); } while (0)
; #define PG8_WAIT_V(n) asm volatile("s_waitcnt vmcnt(" #n ")" ::: "memory")
; #define PG8_WAIT_L(n) asm volatile("s_waitcnt lgkmcnt(" #n ")" ::: "memory")
; #define PG8_BAR __builtin_amdgcn_s_barrier()
; #define PG8_SCHED __builtin_amdgcn_sched_barrier(0)
;     ...
;             PG8_LDB(B0, 0, 0); PG8_LDB(B1, 0, 1); PG8_SCHED; PG8_LDA(At, 0, 0); PG8_STAGE(PG8_SA(1, 1), a1 + hstep, voffA);
;             PG8_WAIT_V(8); PG8_WAIT_L(0); PG8_BAR; PG8_MMA(0, 0, At, B0); PG8_MMA(0, 1, At, B1); PG8_BAR; PG8_SCHED;
;             PG8_LDA(At, 0, 1); PG8_STAGE(PG8_SB(0, 0), b2, voffB); PG8_STAGE(PG8_SB(0, 1), b2 + hstep, voffB); PG8_STAGE(PG8_SA(0, 0), a2, voffA);
.LBB0_335:
	ds_read_b128 v[128:131], v191
	ds_read_b128 v[132:135], v191 offset:1024
	ds_read_b128 v[136:139], v191 offset:2048
	ds_read_b128 v[140:143], v191 offset:3072
	ds_read_b128 v[144:147], v192
	ds_read_b128 v[148:151], v192 offset:1024
	ds_read_b128 v[168:171], v192 offset:2048
	ds_read_b128 v[172:175], v192 offset:3072
	s_add_u32 s33, s50, 0xffea0080
	s_addc_u32 s52, s51, -1
	s_cmpk_eq_i32 s72, 0x54
	s_cselect_b32 s55, s1, s52
	s_cselect_b32 s54, s0, s33
	s_cselect_b32 s53, s49, s35
	s_cselect_b32 s52, s48, s34
	v_lshl_add_u64 v[218:219], s[50:51], 0, v[160:161]
	s_add_i32 m0, s56, 0xc000
	ds_read_b128 v[176:179], v193
	ds_read_b128 v[180:183], v193 offset:1024
	ds_read_b128 v[184:187], v193 offset:2048
	ds_read_b128 v[196:199], v193 offset:3072
	ds_read_b128 v[200:203], v193 offset:4096
	ds_read_b128 v[204:207], v193 offset:5120
	ds_read_b128 v[208:211], v193 offset:6144
	ds_read_b128 v[214:217], v193 offset:7168
	global_load_lds_dwordx4 v[218:219], off
	v_lshl_add_u64 v[218:219], s[50:51], 0, v[162:163]
	s_add_i32 m0, s56, 0xe000
	s_nop 0
	global_load_lds_dwordx4 v[218:219], off
	s_waitcnt vmcnt(8)
	s_waitcnt lgkmcnt(0)
	s_barrier
	v_mfma_f32_16x16x32_bf16 v[124:127], v[128:131], v[176:179], v[124:127]
	v_mfma_f32_16x16x32_bf16 v[124:127], v[132:135], v[180:183], v[124:127]
	v_mfma_f32_16x16x32_bf16 v[120:123], v[136:139], v[176:179], v[120:123]
	v_mfma_f32_16x16x32_bf16 v[120:123], v[140:143], v[180:183], v[120:123]
	v_mfma_f32_16x16x32_bf16 v[108:111], v[128:131], v[184:187], v[108:111]
	v_mfma_f32_16x16x32_bf16 v[108:111], v[132:135], v[196:199], v[108:111]
	v_mfma_f32_16x16x32_bf16 v[104:107], v[136:139], v[184:187], v[104:107]
	v_mfma_f32_16x16x32_bf16 v[104:107], v[140:143], v[196:199], v[104:107]
	v_mfma_f32_16x16x32_bf16 v[92:95], v[128:131], v[200:203], v[92:95]
	v_mfma_f32_16x16x32_bf16 v[92:95], v[132:135], v[204:207], v[92:95]
	v_mfma_f32_16x16x32_bf16 v[88:91], v[136:139], v[200:203], v[88:91]
	v_mfma_f32_16x16x32_bf16 v[88:91], v[140:143], v[204:207], v[88:91]
	v_mfma_f32_16x16x32_bf16 v[76:79], v[128:131], v[208:211], v[76:79]
	v_mfma_f32_16x16x32_bf16 v[76:79], v[132:135], v[214:217], v[76:79]
	v_mfma_f32_16x16x32_bf16 v[72:75], v[136:139], v[208:211], v[72:75]
	v_mfma_f32_16x16x32_bf16 v[72:75], v[140:143], v[214:217], v[72:75]
	v_mfma_f32_16x16x32_bf16 v[116:119], v[144:147], v[176:179], v[116:119]
	v_mfma_f32_16x16x32_bf16 v[116:119], v[148:151], v[180:183], v[116:119]
	v_mfma_f32_16x16x32_bf16 v[112:115], v[168:171], v[176:179], v[112:115]
	v_mfma_f32_16x16x32_bf16 v[112:115], v[172:175], v[180:183], v[112:115]
	v_mfma_f32_16x16x32_bf16 v[100:103], v[144:147], v[184:187], v[100:103]
	v_mfma_f32_16x16x32_bf16 v[100:103], v[148:151], v[196:199], v[100:103]
	v_mfma_f32_16x16x32_bf16 v[96:99], v[168:171], v[184:187], v[96:99]
	v_mfma_f32_16x16x32_bf16 v[96:99], v[172:175], v[196:199], v[96:99]
	v_mfma_f32_16x16x32_bf16 v[84:87], v[144:147], v[200:203], v[84:87]
	v_mfma_f32_16x16x32_bf16 v[84:87], v[148:151], v[204:207], v[84:87]
	v_mfma_f32_16x16x32_bf16 v[80:83], v[168:171], v[200:203], v[80:83]
	v_mfma_f32_16x16x32_bf16 v[80:83], v[172:175], v[204:207], v[80:83]
	v_mfma_f32_16x16x32_bf16 v[68:71], v[144:147], v[208:211], v[68:71]
	v_mfma_f32_16x16x32_bf16 v[68:71], v[148:151], v[214:217], v[68:71]
	v_mfma_f32_16x16x32_bf16 v[64:67], v[168:171], v[208:211], v[64:67]
	v_mfma_f32_16x16x32_bf16 v[64:67], v[172:175], v[214:217], v[64:67]
	s_barrier
	s_add_i32 s33, s66, s19
	v_lshl_add_u64 v[218:219], s[52:53], 0, v[154:155]
	s_mov_b32 m0, s33
	ds_read_b128 v[176:179], v193 offset:16384
	ds_read_b128 v[180:183], v193 offset:17408
	ds_read_b128 v[184:187], v193 offset:18432
	ds_read_b128 v[196:199], v193 offset:19456
	ds_read_b128 v[200:203], v193 offset:20480
	ds_read_b128 v[204:207], v193 offset:21504
	ds_read_b128 v[208:211], v193 offset:22528
	ds_read_b128 v[214:217], v193 offset:23552
	global_load_lds_dwordx4 v[218:219], off
	s_add_i32 m0, s33, 0x2000
	s_add_u32 s74, s52, 0x160000
	v_lshl_add_u64 v[220:221], s[52:53], 0, v[158:159]
	s_addc_u32 s75, s53, 0
	s_add_i32 s33, s67, s19
	global_load_lds_dwordx4 v[220:221], off
	v_lshl_add_u64 v[222:223], s[74:75], 0, v[154:155]
	s_mov_b32 m0, s33
	v_lshl_add_u64 v[224:225], s[54:55], 0, v[156:157]
	global_load_lds_dwordx4 v[222:223], off
	v_lshl_add_u64 v[222:223], s[74:75], 0, v[158:159]
	s_add_i32 m0, s33, 0x2000
	s_nop 0
	global_load_lds_dwordx4 v[222:223], off
	v_lshl_add_u64 v[222:223], s[54:55], 0, v[152:153]
	s_mov_b32 m0, s56
	s_nop 0
	global_load_lds_dwordx4 v[222:223], off
	s_mov_b32 m0, s57
	s_nop 0
	global_load_lds_dwordx4 v[224:225], off
	s_waitcnt vmcnt(8)
	s_waitcnt lgkmcnt(0)
	s_barrier
; #define PG8_STAGE(bufoff, gbase, voff) do { _Pragma("unroll") for (int _i = 0; _i < 2; ++_i) \
;         __builtin_amdgcn_global_load_lds((const unsigned*)((const char*)(gbase) + (voff)[_i]), (PG8_LAS unsigned*)(lds + (bufoff) + ldsw + _i * 8192), 16, 0, 0); } while (0)
; #define PG8_WAIT_V(n) asm volatile("s_waitcnt vmcnt(" #n ")" ::: "memory")
; #define PG8_WAIT_L(n) asm volatile("s_waitcnt lgkmcnt(" #n ")" ::: "memory")
; #define PG8_BAR __builtin_amdgcn_s_barrier()
; #define PG8_SCHED __builtin_amdgcn_sched_barrier(0)
;     ...
;             PG8_WAIT_V(8); PG8_WAIT_L(0); PG8_BAR; PG8_MMA(1, 0, At, B0); PG8_MMA(1, 1, At, B1); PG8_BAR; PG8_SCHED;
;             PG8_LDB(B0, 1, 0); PG8_LDB(B1, 1, 1); PG8_SCHED; PG8_LDA(At, 1, 0); PG8_STAGE(PG8_SA(0, 1), a2 + hstep, voffA);
;             PG8_WAIT_V(8); PG8_WAIT_L(0); PG8_BAR; PG8_MMA(0, 0, At, B0); PG8_MMA(0, 1, At, B1); PG8_BAR; PG8_SCHED;
	v_mfma_f32_16x16x32_bf16 v[60:63], v[128:131], v[176:179], v[60:63]
	v_mfma_f32_16x16x32_bf16 v[60:63], v[132:135], v[180:183], v[60:63]
	v_mfma_f32_16x16x32_bf16 v[56:59], v[136:139], v[176:179], v[56:59]
	v_mfma_f32_16x16x32_bf16 v[56:59], v[140:143], v[180:183], v[56:59]
	v_mfma_f32_16x16x32_bf16 v[44:47], v[128:131], v[184:187], v[44:47]
	v_mfma_f32_16x16x32_bf16 v[44:47], v[132:135], v[196:199], v[44:47]
	v_mfma_f32_16x16x32_bf16 v[40:43], v[136:139], v[184:187], v[40:43]
	v_mfma_f32_16x16x32_bf16 v[40:43], v[140:143], v[196:199], v[40:43]
	v_mfma_f32_16x16x32_bf16 v[28:31], v[128:131], v[200:203], v[28:31]
	v_mfma_f32_16x16x32_bf16 v[28:31], v[132:135], v[204:207], v[28:31]
	v_mfma_f32_16x16x32_bf16 v[24:27], v[136:139], v[200:203], v[24:27]
	v_mfma_f32_16x16x32_bf16 v[24:27], v[140:143], v[204:207], v[24:27]
	v_mfma_f32_16x16x32_bf16 v[12:15], v[128:131], v[208:211], v[12:15]
	v_mfma_f32_16x16x32_bf16 v[12:15], v[132:135], v[214:217], v[12:15]
	v_mfma_f32_16x16x32_bf16 v[8:11], v[136:139], v[208:211], v[8:11]
	v_mfma_f32_16x16x32_bf16 v[8:11], v[140:143], v[214:217], v[8:11]
	v_mfma_f32_16x16x32_bf16 v[52:55], v[144:147], v[176:179], v[52:55]
	v_mfma_f32_16x16x32_bf16 v[52:55], v[148:151], v[180:183], v[52:55]
	v_mfma_f32_16x16x32_bf16 v[48:51], v[168:171], v[176:179], v[48:51]
	v_mfma_f32_16x16x32_bf16 v[48:51], v[172:175], v[180:183], v[48:51]
	v_mfma_f32_16x16x32_bf16 v[36:39], v[144:147], v[184:187], v[36:39]
	v_mfma_f32_16x16x32_bf16 v[36:39], v[148:151], v[196:199], v[36:39]
	v_mfma_f32_16x16x32_bf16 v[32:35], v[168:171], v[184:187], v[32:35]
	v_mfma_f32_16x16x32_bf16 v[32:35], v[172:175], v[196:199], v[32:35]
	v_mfma_f32_16x16x32_bf16 v[20:23], v[144:147], v[200:203], v[20:23]
	v_mfma_f32_16x16x32_bf16 v[20:23], v[148:151], v[204:207], v[20:23]
	v_mfma_f32_16x16x32_bf16 v[16:19], v[168:171], v[200:203], v[16:19]
	v_mfma_f32_16x16x32_bf16 v[16:19], v[172:175], v[204:207], v[16:19]
	v_mfma_f32_16x16x32_bf16 v[4:7], v[144:147], v[208:211], v[4:7]
	v_mfma_f32_16x16x32_bf16 v[4:7], v[148:151], v[214:217], v[4:7]
	v_mfma_f32_16x16x32_bf16 v[0:3], v[168:171], v[208:211], v[0:3]
	v_mfma_f32_16x16x32_bf16 v[0:3], v[172:175], v[214:217], v[0:3]
	s_barrier
	s_add_i32 s33, 0, 0x18000
	s_add_i32 s73, 0, 0x1c000
	v_add_u32_e32 v140, s33, v189
	v_add_u32_e32 v172, s73, v189
	ds_read_b128 v[128:131], v140
	ds_read_b128 v[132:135], v140 offset:1024
	ds_read_b128 v[136:139], v140 offset:2048
	ds_read_b128 v[140:143], v140 offset:3072
	ds_read_b128 v[144:147], v172
	ds_read_b128 v[148:151], v172 offset:1024
	ds_read_b128 v[168:171], v172 offset:2048
	ds_read_b128 v[172:175], v172 offset:3072
	s_add_u32 s54, s54, 0x160000
	s_addc_u32 s55, s55, 0
	s_mov_b32 m0, s58
	v_lshl_add_u64 v[226:227], s[54:55], 0, v[152:153]
	ds_read_b128 v[176:179], v193 offset:32768
	ds_read_b128 v[180:183], v193 offset:33792
	ds_read_b128 v[184:187], v193 offset:34816
	ds_read_b128 v[196:199], v193 offset:35840
	ds_read_b128 v[200:203], v193 offset:36864
	ds_read_b128 v[204:207], v193 offset:37888
	ds_read_b128 v[208:211], v193 offset:38912
	ds_read_b128 v[214:217], v193 offset:39936
	global_load_lds_dwordx4 v[226:227], off
	v_lshl_add_u64 v[226:227], s[54:55], 0, v[156:157]
	s_mov_b32 m0, s59
	s_nop 0
	global_load_lds_dwordx4 v[226:227], off
	s_waitcnt vmcnt(8)
	s_waitcnt lgkmcnt(0)
	s_barrier
	v_mfma_f32_16x16x32_bf16 v[124:127], v[128:131], v[176:179], v[124:127]
	v_mfma_f32_16x16x32_bf16 v[124:127], v[132:135], v[180:183], v[124:127]
	v_mfma_f32_16x16x32_bf16 v[120:123], v[136:139], v[176:179], v[120:123]
	v_mfma_f32_16x16x32_bf16 v[120:123], v[140:143], v[180:183], v[120:123]
	v_mfma_f32_16x16x32_bf16 v[108:111], v[128:131], v[184:187], v[108:111]
	v_mfma_f32_16x16x32_bf16 v[108:111], v[132:135], v[196:199], v[108:111]
	v_mfma_f32_16x16x32_bf16 v[104:107], v[136:139], v[184:187], v[104:107]
	v_mfma_f32_16x16x32_bf16 v[104:107], v[140:143], v[196:199], v[104:107]
	v_mfma_f32_16x16x32_bf16 v[92:95], v[128:131], v[200:203], v[92:95]
	v_mfma_f32_16x16x32_bf16 v[92:95], v[132:135], v[204:207], v[92:95]
	v_mfma_f32_16x16x32_bf16 v[88:91], v[136:139], v[200:203], v[88:91]
	v_mfma_f32_16x16x32_bf16 v[88:91], v[140:143], v[204:207], v[88:91]
	v_mfma_f32_16x16x32_bf16 v[76:79], v[128:131], v[208:211], v[76:79]
	v_mfma_f32_16x16x32_bf16 v[76:79], v[132:135], v[214:217], v[76:79]
	v_mfma_f32_16x16x32_bf16 v[72:75], v[136:139], v[208:211], v[72:75]
	v_mfma_f32_16x16x32_bf16 v[72:75], v[140:143], v[214:217], v[72:75]
	v_mfma_f32_16x16x32_bf16 v[116:119], v[144:147], v[176:179], v[116:119]
	v_mfma_f32_16x16x32_bf16 v[116:119], v[148:151], v[180:183], v[116:119]
	v_mfma_f32_16x16x32_bf16 v[112:115], v[168:171], v[176:179], v[112:115]
	v_mfma_f32_16x16x32_bf16 v[112:115], v[172:175], v[180:183], v[112:115]
	v_mfma_f32_16x16x32_bf16 v[100:103], v[144:147], v[184:187], v[100:103]
	v_mfma_f32_16x16x32_bf16 v[100:103], v[148:151], v[196:199], v[100:103]
	v_mfma_f32_16x16x32_bf16 v[96:99], v[168:171], v[184:187], v[96:99]
	v_mfma_f32_16x16x32_bf16 v[96:99], v[172:175], v[196:199], v[96:99]
	v_mfma_f32_16x16x32_bf16 v[84:87], v[144:147], v[200:203], v[84:87]
	v_mfma_f32_16x16x32_bf16 v[84:87], v[148:151], v[204:207], v[84:87]
	v_mfma_f32_16x16x32_bf16 v[80:83], v[168:171], v[200:203], v[80:83]
	v_mfma_f32_16x16x32_bf16 v[80:83], v[172:175], v[204:207], v[80:83]
	v_mfma_f32_16x16x32_bf16 v[68:71], v[144:147], v[208:211], v[68:71]
	v_mfma_f32_16x16x32_bf16 v[68:71], v[148:151], v[214:217], v[68:71]
	v_mfma_f32_16x16x32_bf16 v[64:67], v[168:171], v[208:211], v[64:67]
	v_mfma_f32_16x16x32_bf16 v[64:67], v[172:175], v[214:217], v[64:67]
	s_barrier
; #define PG8_STAGE(bufoff, gbase, voff) do { _Pragma("unroll") for (int _i = 0; _i < 2; ++_i) \
;         __builtin_amdgcn_global_load_lds((const unsigned*)((const char*)(gbase) + (voff)[_i]), (PG8_LAS unsigned*)(lds + (bufoff) + ldsw + _i * 8192), 16, 0, 0); } while (0)
; #define PG8_WAIT_V(n) asm volatile("s_waitcnt vmcnt(" #n ")" ::: "memory")
; #define PG8_WAIT_L(n) asm volatile("s_waitcnt lgkmcnt(" #n ")" ::: "memory")
; #define PG8_BAR __builtin_amdgcn_s_barrier()
; #define PG8_SCHED __builtin_amdgcn_sched_barrier(0)
;     ...
;             PG8_LDA(At, 1, 1); PG8_STAGE(PG8_SB(1, 0), b3, voffB); PG8_STAGE(PG8_SB(1, 1), b3 + hstep, voffB); PG8_STAGE(PG8_SA(1, 0), a3, voffA);
;             PG8_WAIT_V(8); PG8_WAIT_L(0); PG8_BAR; PG8_MMA(1, 0, At, B0); PG8_MMA(1, 1, At, B1); PG8_BAR; PG8_SCHED;
;     ...
;         if constexpr (ALIGN_EPI) { if (wr == 0) PG8_BAR; }
	s_add_i32 s33, s33, s19
	v_lshl_add_u64 v[218:219], v[218:219], 0, s[24:25]
	s_mov_b32 m0, s33
	ds_read_b128 v[176:179], v193 offset:49152
	ds_read_b128 v[180:183], v193 offset:50176
	ds_read_b128 v[184:187], v193 offset:51200
	ds_read_b128 v[196:199], v193 offset:52224
	ds_read_b128 v[200:203], v193 offset:53248
	ds_read_b128 v[204:207], v193 offset:54272
	ds_read_b128 v[208:211], v193 offset:55296
	ds_read_b128 v[214:217], v193 offset:56320
	global_load_lds_dwordx4 v[218:219], off
	s_add_i32 m0, s33, 0x2000
	s_add_u32 s52, s52, 0x160080
	v_lshl_add_u64 v[218:219], v[220:221], 0, s[24:25]
	s_addc_u32 s53, s53, 0
	s_add_i32 s33, s73, s19
	global_load_lds_dwordx4 v[218:219], off
	v_lshl_add_u64 v[218:219], s[52:53], 0, v[154:155]
	s_mov_b32 m0, s33
	s_nop 0
	global_load_lds_dwordx4 v[218:219], off
	v_lshl_add_u64 v[218:219], s[52:53], 0, v[158:159]
	s_add_i32 m0, s33, 0x2000
	s_nop 0
	global_load_lds_dwordx4 v[218:219], off
	v_lshl_add_u64 v[218:219], v[222:223], 0, s[24:25]
	s_mov_b32 m0, s61
	s_nop 0
	global_load_lds_dwordx4 v[218:219], off
	v_lshl_add_u64 v[218:219], v[224:225], 0, s[24:25]
	s_mov_b32 m0, s62
	s_nop 0
	global_load_lds_dwordx4 v[218:219], off
	s_waitcnt vmcnt(8)
	s_waitcnt lgkmcnt(0)
	s_barrier
	v_mfma_f32_16x16x32_bf16 v[60:63], v[128:131], v[176:179], v[60:63]
	v_mfma_f32_16x16x32_bf16 v[60:63], v[132:135], v[180:183], v[60:63]
	v_mfma_f32_16x16x32_bf16 v[56:59], v[136:139], v[176:179], v[56:59]
	v_mfma_f32_16x16x32_bf16 v[56:59], v[140:143], v[180:183], v[56:59]
	v_mfma_f32_16x16x32_bf16 v[44:47], v[128:131], v[184:187], v[44:47]
	v_mfma_f32_16x16x32_bf16 v[44:47], v[132:135], v[196:199], v[44:47]
	v_mfma_f32_16x16x32_bf16 v[40:43], v[136:139], v[184:187], v[40:43]
	v_mfma_f32_16x16x32_bf16 v[40:43], v[140:143], v[196:199], v[40:43]
	v_mfma_f32_16x16x32_bf16 v[28:31], v[128:131], v[200:203], v[28:31]
	v_mfma_f32_16x16x32_bf16 v[28:31], v[132:135], v[204:207], v[28:31]
	v_mfma_f32_16x16x32_bf16 v[24:27], v[136:139], v[200:203], v[24:27]
	v_mfma_f32_16x16x32_bf16 v[24:27], v[140:143], v[204:207], v[24:27]
	v_mfma_f32_16x16x32_bf16 v[12:15], v[128:131], v[208:211], v[12:15]
	v_mfma_f32_16x16x32_bf16 v[12:15], v[132:135], v[214:217], v[12:15]
	v_mfma_f32_16x16x32_bf16 v[8:11], v[136:139], v[208:211], v[8:11]
	v_mfma_f32_16x16x32_bf16 v[8:11], v[140:143], v[214:217], v[8:11]
	v_mfma_f32_16x16x32_bf16 v[52:55], v[144:147], v[176:179], v[52:55]
	v_mfma_f32_16x16x32_bf16 v[52:55], v[148:151], v[180:183], v[52:55]
	v_mfma_f32_16x16x32_bf16 v[48:51], v[168:171], v[176:179], v[48:51]
	v_mfma_f32_16x16x32_bf16 v[48:51], v[172:175], v[180:183], v[48:51]
	v_mfma_f32_16x16x32_bf16 v[36:39], v[144:147], v[184:187], v[36:39]
	v_mfma_f32_16x16x32_bf16 v[36:39], v[148:151], v[196:199], v[36:39]
	v_mfma_f32_16x16x32_bf16 v[32:35], v[168:171], v[184:187], v[32:35]
	v_mfma_f32_16x16x32_bf16 v[32:35], v[172:175], v[196:199], v[32:35]
	v_mfma_f32_16x16x32_bf16 v[20:23], v[144:147], v[200:203], v[20:23]
	v_mfma_f32_16x16x32_bf16 v[20:23], v[148:151], v[204:207], v[20:23]
	v_mfma_f32_16x16x32_bf16 v[16:19], v[168:171], v[200:203], v[16:19]
	v_mfma_f32_16x16x32_bf16 v[16:19], v[172:175], v[204:207], v[16:19]
	v_mfma_f32_16x16x32_bf16 v[4:7], v[144:147], v[208:211], v[4:7]
	v_mfma_f32_16x16x32_bf16 v[4:7], v[148:151], v[214:217], v[4:7]
	v_mfma_f32_16x16x32_bf16 v[0:3], v[168:171], v[208:211], v[0:3]
	v_mfma_f32_16x16x32_bf16 v[0:3], v[172:175], v[214:217], v[0:3]
	s_barrier
	s_add_i32 s72, s72, 2
	s_add_u32 s50, s50, 0x100
	s_addc_u32 s51, s51, 0
	s_add_u32 s34, s34, 0x100
	s_addc_u32 s35, s35, 0
	s_cmpk_gt_u32 s72, 0x55
	s_cbranch_scc0 .LBB0_335
	s_and_b64 vcc, exec, s[44:45]
	s_cbranch_vccz .LBB0_338
	s_barrier

; #define PG8_STAGE(bufoff, gbase, voff) do { _Pragma("unroll") for (int _i = 0; _i < 2; ++_i) \
;         __builtin_amdgcn_global_load_lds((const unsigned*)((const char*)(gbase) + (voff)[_i]), (PG8_LAS unsigned*)(lds + (bufoff) + ldsw + _i * 8192), 16, 0, 0); } while (0)
; #define PG8_WAIT_V(n) asm volatile("s_waitcnt vmcnt(" #n ")" ::: "memory")
; #define PG8_WAIT_L(n) asm volatile("s_waitcnt lgkmcnt(" #n ")" ::: "memory")
; #define PG8_BAR __builtin_amdgcn_s_barrier()
; #define PG8_SCHED __builtin_amdgcn_sched_barrier(0)
;     ...
;             PG8_LDB(B0, 0, 0); PG8_LDB(B1, 0, 1); PG8_SCHED; PG8_LDA(At, 0, 0); PG8_STAGE(PG8_SA(1, 1), a1 + hstep, voffA);
;             PG8_WAIT_V(8); PG8_WAIT_L(0); PG8_BAR; PG8_MMA(0, 0, At, B0); PG8_MMA(0, 1, At, B1); PG8_BAR; PG8_SCHED;
;             PG8_LDA(At, 0, 1); PG8_STAGE(PG8_SB(0, 0), b2, voffB); PG8_STAGE(PG8_SB(0, 1), b2 + hstep, voffB); PG8_STAGE(PG8_SA(0, 0), a2, voffA);
.LBB0_432:
	v_add_u32_e32 v142, s91, v205
	v_add_u32_e32 v146, s92, v205
	ds_read_b128 v[130:133], v142
	ds_read_b128 v[134:137], v142 offset:1024
	s_waitcnt lgkmcnt(0)
	ds_read_b128 v[138:141], v142 offset:2048
	ds_read_b128 v[142:145], v142 offset:3072
	ds_read_b128 v[188:191], v146
	ds_read_b128 v[192:195], v146 offset:1024
	ds_read_b128 v[196:199], v146 offset:2048
	ds_read_b128 v[200:203], v146 offset:3072
	s_add_u32 s33, s70, 0xfff80080
	s_addc_u32 s74, s71, -1
	s_and_b64 s[72:73], s[72:73], exec
	s_cselect_b32 s75, s18, s74
	s_cselect_b32 s74, s19, s33
	s_cselect_b32 s73, s34, s61
	s_cselect_b32 s72, s35, s10
	v_lshl_add_u64 v[146:147], s[70:71], 0, v[162:163]
	s_add_i32 m0, s69, 0xc000
	ds_read_b128 v[214:217], v159
	ds_read_b128 v[218:221], v159 offset:1024
	ds_read_b128 v[222:225], v159 offset:2048
	ds_read_b128 v[226:229], v159 offset:3072
	ds_read_b128 v[230:233], v159 offset:4096
	ds_read_b128 v[234:237], v159 offset:5120
	ds_read_b128 v[238:241], v159 offset:6144
	ds_read_b128 v[242:245], v159 offset:7168
	global_load_lds_dwordx4 v[146:147], off
	v_lshl_add_u64 v[146:147], s[70:71], 0, v[164:165]
	s_add_i32 m0, s69, 0xe000
	s_nop 0
	global_load_lds_dwordx4 v[146:147], off
	s_waitcnt vmcnt(8)
	s_waitcnt lgkmcnt(0)
	s_barrier
	v_mfma_f32_16x16x32_bf16 v[124:127], v[130:133], v[214:217], v[124:127]
	v_mfma_f32_16x16x32_bf16 v[124:127], v[134:137], v[218:221], v[124:127]
	v_mfma_f32_16x16x32_bf16 v[120:123], v[138:141], v[214:217], v[120:123]
	v_mfma_f32_16x16x32_bf16 v[120:123], v[142:145], v[218:221], v[120:123]
	v_mfma_f32_16x16x32_bf16 v[108:111], v[130:133], v[222:225], v[108:111]
	v_mfma_f32_16x16x32_bf16 v[108:111], v[134:137], v[226:229], v[108:111]
	v_mfma_f32_16x16x32_bf16 v[104:107], v[138:141], v[222:225], v[104:107]
	v_mfma_f32_16x16x32_bf16 v[104:107], v[142:145], v[226:229], v[104:107]
	v_mfma_f32_16x16x32_bf16 v[92:95], v[130:133], v[230:233], v[92:95]
	v_mfma_f32_16x16x32_bf16 v[92:95], v[134:137], v[234:237], v[92:95]
	v_mfma_f32_16x16x32_bf16 v[88:91], v[138:141], v[230:233], v[88:91]
	v_mfma_f32_16x16x32_bf16 v[88:91], v[142:145], v[234:237], v[88:91]
	v_mfma_f32_16x16x32_bf16 v[76:79], v[130:133], v[238:241], v[76:79]
	v_mfma_f32_16x16x32_bf16 v[76:79], v[134:137], v[242:245], v[76:79]
	v_mfma_f32_16x16x32_bf16 v[72:75], v[138:141], v[238:241], v[72:75]
	v_mfma_f32_16x16x32_bf16 v[72:75], v[142:145], v[242:245], v[72:75]
	v_mfma_f32_16x16x32_bf16 v[116:119], v[188:191], v[214:217], v[116:119]
	v_mfma_f32_16x16x32_bf16 v[116:119], v[192:195], v[218:221], v[116:119]
	v_mfma_f32_16x16x32_bf16 v[112:115], v[196:199], v[214:217], v[112:115]
	v_mfma_f32_16x16x32_bf16 v[112:115], v[200:203], v[218:221], v[112:115]
	v_mfma_f32_16x16x32_bf16 v[100:103], v[188:191], v[222:225], v[100:103]
	v_mfma_f32_16x16x32_bf16 v[100:103], v[192:195], v[226:229], v[100:103]
	v_mfma_f32_16x16x32_bf16 v[96:99], v[196:199], v[222:225], v[96:99]
	v_mfma_f32_16x16x32_bf16 v[96:99], v[200:203], v[226:229], v[96:99]
	v_mfma_f32_16x16x32_bf16 v[84:87], v[188:191], v[230:233], v[84:87]
	v_mfma_f32_16x16x32_bf16 v[84:87], v[192:195], v[234:237], v[84:87]
	v_mfma_f32_16x16x32_bf16 v[80:83], v[196:199], v[230:233], v[80:83]
	v_mfma_f32_16x16x32_bf16 v[80:83], v[200:203], v[234:237], v[80:83]
	v_mfma_f32_16x16x32_bf16 v[68:71], v[188:191], v[238:241], v[68:71]
	v_mfma_f32_16x16x32_bf16 v[68:71], v[192:195], v[242:245], v[68:71]
	v_mfma_f32_16x16x32_bf16 v[64:67], v[196:199], v[238:241], v[64:67]
	v_mfma_f32_16x16x32_bf16 v[64:67], v[200:203], v[242:245], v[64:67]
	s_barrier
	s_add_i32 s33, s91, s82
	v_lshl_add_u64 v[146:147], s[72:73], 0, v[150:151]
	s_mov_b32 m0, s33
	ds_read_b128 v[214:217], v159 offset:16384
	ds_read_b128 v[218:221], v159 offset:17408
	ds_read_b128 v[222:225], v159 offset:18432
	ds_read_b128 v[226:229], v159 offset:19456
	ds_read_b128 v[230:233], v159 offset:20480
	ds_read_b128 v[234:237], v159 offset:21504
	ds_read_b128 v[238:241], v159 offset:22528
	ds_read_b128 v[242:245], v159 offset:23552
	global_load_lds_dwordx4 v[146:147], off
	s_add_i32 m0, s33, 0x2000
	s_add_u32 s94, s72, 0x80000
	v_lshl_add_u64 v[246:247], s[72:73], 0, v[154:155]
	s_addc_u32 s95, s73, 0
	s_add_i32 s33, s92, s82
	global_load_lds_dwordx4 v[246:247], off
	v_lshl_add_u64 v[248:249], s[94:95], 0, v[150:151]
	s_mov_b32 m0, s33
	v_lshl_add_u64 v[250:251], s[74:75], 0, v[152:153]
	global_load_lds_dwordx4 v[248:249], off
	v_lshl_add_u64 v[248:249], s[94:95], 0, v[154:155]
	s_add_i32 m0, s33, 0x2000
	s_nop 0
	global_load_lds_dwordx4 v[248:249], off
	v_lshl_add_u64 v[248:249], s[74:75], 0, v[148:149]
	s_mov_b32 m0, s69
	s_nop 0
	global_load_lds_dwordx4 v[248:249], off
	s_mov_b32 m0, s83
	s_nop 0
	global_load_lds_dwordx4 v[250:251], off
	s_waitcnt vmcnt(8)
	s_waitcnt lgkmcnt(0)
	s_barrier
; #define PG8_STAGE(bufoff, gbase, voff) do { _Pragma("unroll") for (int _i = 0; _i < 2; ++_i) \
;         __builtin_amdgcn_global_load_lds((const unsigned*)((const char*)(gbase) + (voff)[_i]), (PG8_LAS unsigned*)(lds + (bufoff) + ldsw + _i * 8192), 16, 0, 0); } while (0)
; #define PG8_WAIT_V(n) asm volatile("s_waitcnt vmcnt(" #n ")" ::: "memory")
; #define PG8_WAIT_L(n) asm volatile("s_waitcnt lgkmcnt(" #n ")" ::: "memory")
; #define PG8_BAR __builtin_amdgcn_s_barrier()
; #define PG8_SCHED __builtin_amdgcn_sched_barrier(0)
;     ...
;             PG8_WAIT_V(8); PG8_WAIT_L(0); PG8_BAR; PG8_MMA(1, 0, At, B0); PG8_MMA(1, 1, At, B1); PG8_BAR; PG8_SCHED;
;             PG8_LDB(B0, 1, 0); PG8_LDB(B1, 1, 1); PG8_SCHED; PG8_LDA(At, 1, 0); PG8_STAGE(PG8_SA(0, 1), a2 + hstep, voffA);
;             PG8_WAIT_V(8); PG8_WAIT_L(0); PG8_BAR; PG8_MMA(0, 0, At, B0); PG8_MMA(0, 1, At, B1); PG8_BAR; PG8_SCHED;
	v_mfma_f32_16x16x32_bf16 v[60:63], v[130:133], v[214:217], v[60:63]
	v_mfma_f32_16x16x32_bf16 v[60:63], v[134:137], v[218:221], v[60:63]
	v_mfma_f32_16x16x32_bf16 v[56:59], v[138:141], v[214:217], v[56:59]
	v_mfma_f32_16x16x32_bf16 v[56:59], v[142:145], v[218:221], v[56:59]
	v_mfma_f32_16x16x32_bf16 v[44:47], v[130:133], v[222:225], v[44:47]
	v_mfma_f32_16x16x32_bf16 v[44:47], v[134:137], v[226:229], v[44:47]
	v_mfma_f32_16x16x32_bf16 v[40:43], v[138:141], v[222:225], v[40:43]
	v_mfma_f32_16x16x32_bf16 v[40:43], v[142:145], v[226:229], v[40:43]
	v_mfma_f32_16x16x32_bf16 v[28:31], v[130:133], v[230:233], v[28:31]
	v_mfma_f32_16x16x32_bf16 v[28:31], v[134:137], v[234:237], v[28:31]
	v_mfma_f32_16x16x32_bf16 v[24:27], v[138:141], v[230:233], v[24:27]
	v_mfma_f32_16x16x32_bf16 v[24:27], v[142:145], v[234:237], v[24:27]
	v_mfma_f32_16x16x32_bf16 v[12:15], v[130:133], v[238:241], v[12:15]
	v_mfma_f32_16x16x32_bf16 v[12:15], v[134:137], v[242:245], v[12:15]
	v_mfma_f32_16x16x32_bf16 v[8:11], v[138:141], v[238:241], v[8:11]
	v_mfma_f32_16x16x32_bf16 v[8:11], v[142:145], v[242:245], v[8:11]
	v_mfma_f32_16x16x32_bf16 v[52:55], v[188:191], v[214:217], v[52:55]
	v_mfma_f32_16x16x32_bf16 v[52:55], v[192:195], v[218:221], v[52:55]
	v_mfma_f32_16x16x32_bf16 v[48:51], v[196:199], v[214:217], v[48:51]
	v_mfma_f32_16x16x32_bf16 v[48:51], v[200:203], v[218:221], v[48:51]
	v_mfma_f32_16x16x32_bf16 v[36:39], v[188:191], v[222:225], v[36:39]
	v_mfma_f32_16x16x32_bf16 v[36:39], v[192:195], v[226:229], v[36:39]
	v_mfma_f32_16x16x32_bf16 v[32:35], v[196:199], v[222:225], v[32:35]
	v_mfma_f32_16x16x32_bf16 v[32:35], v[200:203], v[226:229], v[32:35]
	v_mfma_f32_16x16x32_bf16 v[20:23], v[188:191], v[230:233], v[20:23]
	v_mfma_f32_16x16x32_bf16 v[20:23], v[192:195], v[234:237], v[20:23]
	v_mfma_f32_16x16x32_bf16 v[16:19], v[196:199], v[230:233], v[16:19]
	v_mfma_f32_16x16x32_bf16 v[16:19], v[200:203], v[234:237], v[16:19]
	v_mfma_f32_16x16x32_bf16 v[4:7], v[188:191], v[238:241], v[4:7]
	v_mfma_f32_16x16x32_bf16 v[4:7], v[192:195], v[242:245], v[4:7]
	v_mfma_f32_16x16x32_bf16 v[0:3], v[196:199], v[238:241], v[0:3]
	v_mfma_f32_16x16x32_bf16 v[0:3], v[200:203], v[242:245], v[0:3]
	s_barrier
	s_add_i32 s33, 0, 0x18000
	s_add_i32 s94, 0, 0x1c000
	v_add_u32_e32 v142, s33, v205
	v_add_u32_e32 v156, s94, v205
	ds_read_b128 v[130:133], v142
	ds_read_b128 v[134:137], v142 offset:1024
	ds_read_b128 v[138:141], v142 offset:2048
	ds_read_b128 v[142:145], v142 offset:3072
	ds_read_b128 v[188:191], v156
	ds_read_b128 v[192:195], v156 offset:1024
	ds_read_b128 v[196:199], v156 offset:2048
	ds_read_b128 v[200:203], v156 offset:3072
	s_add_u32 s74, s74, 0x80000
	s_addc_u32 s75, s75, 0
	s_mov_b32 m0, s84
	v_lshl_add_u64 v[252:253], s[74:75], 0, v[148:149]
	ds_read_b128 v[214:217], v159 offset:32768
	ds_read_b128 v[218:221], v159 offset:33792
	ds_read_b128 v[222:225], v159 offset:34816
	ds_read_b128 v[226:229], v159 offset:35840
	ds_read_b128 v[230:233], v159 offset:36864
	ds_read_b128 v[234:237], v159 offset:37888
	ds_read_b128 v[238:241], v159 offset:38912
	ds_read_b128 v[242:245], v159 offset:39936
	global_load_lds_dwordx4 v[252:253], off
	v_lshl_add_u64 v[252:253], s[74:75], 0, v[152:153]
	s_mov_b32 m0, s85
	s_nop 0
	global_load_lds_dwordx4 v[252:253], off
	s_waitcnt vmcnt(8)
	s_waitcnt lgkmcnt(0)
	s_barrier
	v_mfma_f32_16x16x32_bf16 v[124:127], v[130:133], v[214:217], v[124:127]
	v_mfma_f32_16x16x32_bf16 v[124:127], v[134:137], v[218:221], v[124:127]
	v_mfma_f32_16x16x32_bf16 v[120:123], v[138:141], v[214:217], v[120:123]
	v_mfma_f32_16x16x32_bf16 v[120:123], v[142:145], v[218:221], v[120:123]
	v_mfma_f32_16x16x32_bf16 v[108:111], v[130:133], v[222:225], v[108:111]
	v_mfma_f32_16x16x32_bf16 v[108:111], v[134:137], v[226:229], v[108:111]
	v_mfma_f32_16x16x32_bf16 v[104:107], v[138:141], v[222:225], v[104:107]
	v_mfma_f32_16x16x32_bf16 v[104:107], v[142:145], v[226:229], v[104:107]
	v_mfma_f32_16x16x32_bf16 v[92:95], v[130:133], v[230:233], v[92:95]
	v_mfma_f32_16x16x32_bf16 v[92:95], v[134:137], v[234:237], v[92:95]
	v_mfma_f32_16x16x32_bf16 v[88:91], v[138:141], v[230:233], v[88:91]
	v_mfma_f32_16x16x32_bf16 v[88:91], v[142:145], v[234:237], v[88:91]
	v_mfma_f32_16x16x32_bf16 v[76:79], v[130:133], v[238:241], v[76:79]
	v_mfma_f32_16x16x32_bf16 v[76:79], v[134:137], v[242:245], v[76:79]
	v_mfma_f32_16x16x32_bf16 v[72:75], v[138:141], v[238:241], v[72:75]
	v_mfma_f32_16x16x32_bf16 v[72:75], v[142:145], v[242:245], v[72:75]
	v_mfma_f32_16x16x32_bf16 v[116:119], v[188:191], v[214:217], v[116:119]
	v_mfma_f32_16x16x32_bf16 v[116:119], v[192:195], v[218:221], v[116:119]
	v_mfma_f32_16x16x32_bf16 v[112:115], v[196:199], v[214:217], v[112:115]
	v_mfma_f32_16x16x32_bf16 v[112:115], v[200:203], v[218:221], v[112:115]
	v_mfma_f32_16x16x32_bf16 v[100:103], v[188:191], v[222:225], v[100:103]
	v_mfma_f32_16x16x32_bf16 v[100:103], v[192:195], v[226:229], v[100:103]
	v_mfma_f32_16x16x32_bf16 v[96:99], v[196:199], v[222:225], v[96:99]
	v_mfma_f32_16x16x32_bf16 v[96:99], v[200:203], v[226:229], v[96:99]
	v_mfma_f32_16x16x32_bf16 v[84:87], v[188:191], v[230:233], v[84:87]
	v_mfma_f32_16x16x32_bf16 v[84:87], v[192:195], v[234:237], v[84:87]
	v_mfma_f32_16x16x32_bf16 v[80:83], v[196:199], v[230:233], v[80:83]
	v_mfma_f32_16x16x32_bf16 v[80:83], v[200:203], v[234:237], v[80:83]
	v_mfma_f32_16x16x32_bf16 v[68:71], v[188:191], v[238:241], v[68:71]
	v_mfma_f32_16x16x32_bf16 v[68:71], v[192:195], v[242:245], v[68:71]
	v_mfma_f32_16x16x32_bf16 v[64:67], v[196:199], v[238:241], v[64:67]
	v_mfma_f32_16x16x32_bf16 v[64:67], v[200:203], v[242:245], v[64:67]
	s_barrier
; #define PG8_STAGE(bufoff, gbase, voff) do { _Pragma("unroll") for (int _i = 0; _i < 2; ++_i) \
;         __builtin_amdgcn_global_load_lds((const unsigned*)((const char*)(gbase) + (voff)[_i]), (PG8_LAS unsigned*)(lds + (bufoff) + ldsw + _i * 8192), 16, 0, 0); } while (0)
; #define PG8_WAIT_V(n) asm volatile("s_waitcnt vmcnt(" #n ")" ::: "memory")
; #define PG8_WAIT_L(n) asm volatile("s_waitcnt lgkmcnt(" #n ")" ::: "memory")
; #define PG8_BAR __builtin_amdgcn_s_barrier()
; #define PG8_SCHED __builtin_amdgcn_sched_barrier(0)
;     ...
;         for (int t = 0; t < nt; t += 2) {
;     ...
;             PG8_LDA(At, 1, 1); PG8_STAGE(PG8_SB(1, 0), b3, voffB); PG8_STAGE(PG8_SB(1, 1), b3 + hstep, voffB); PG8_STAGE(PG8_SA(1, 0), a3, voffA);
;             PG8_WAIT_V(8); PG8_WAIT_L(0); PG8_BAR; PG8_MMA(1, 0, At, B0); PG8_MMA(1, 1, At, B1); PG8_BAR; PG8_SCHED;
	s_add_i32 s33, s33, s82
	v_lshl_add_u64 v[146:147], v[146:147], 0, s[50:51]
	s_mov_b32 m0, s33
	ds_read_b128 v[214:217], v159 offset:49152
	ds_read_b128 v[218:221], v159 offset:50176
	ds_read_b128 v[222:225], v159 offset:51200
	ds_read_b128 v[226:229], v159 offset:52224
	ds_read_b128 v[230:233], v159 offset:53248
	ds_read_b128 v[234:237], v159 offset:54272
	ds_read_b128 v[238:241], v159 offset:55296
	ds_read_b128 v[242:245], v159 offset:56320
	global_load_lds_dwordx4 v[146:147], off
	s_add_i32 m0, s33, 0x2000
	s_add_u32 s72, s72, 0x80080
	v_lshl_add_u64 v[146:147], v[246:247], 0, s[50:51]
	s_addc_u32 s73, s73, 0
	s_add_i32 s33, s94, s82
	global_load_lds_dwordx4 v[146:147], off
	v_lshl_add_u64 v[146:147], s[72:73], 0, v[150:151]
	s_mov_b32 m0, s33
	s_nop 0
	global_load_lds_dwordx4 v[146:147], off
	v_lshl_add_u64 v[146:147], s[72:73], 0, v[154:155]
	s_add_i32 m0, s33, 0x2000
	s_nop 0
	global_load_lds_dwordx4 v[146:147], off
	v_lshl_add_u64 v[146:147], v[248:249], 0, s[50:51]
	s_mov_b32 m0, s86
	s_nop 0
	global_load_lds_dwordx4 v[146:147], off
	v_lshl_add_u64 v[146:147], v[250:251], 0, s[50:51]
	s_mov_b32 m0, s87
	s_nop 0
	global_load_lds_dwordx4 v[146:147], off
	s_waitcnt vmcnt(8)
	s_waitcnt lgkmcnt(0)
	s_barrier
	v_mfma_f32_16x16x32_bf16 v[60:63], v[130:133], v[214:217], v[60:63]
	v_mfma_f32_16x16x32_bf16 v[60:63], v[134:137], v[218:221], v[60:63]
	v_mfma_f32_16x16x32_bf16 v[56:59], v[138:141], v[214:217], v[56:59]
	v_mfma_f32_16x16x32_bf16 v[56:59], v[142:145], v[218:221], v[56:59]
	v_mfma_f32_16x16x32_bf16 v[44:47], v[130:133], v[222:225], v[44:47]
	v_mfma_f32_16x16x32_bf16 v[44:47], v[134:137], v[226:229], v[44:47]
	v_mfma_f32_16x16x32_bf16 v[40:43], v[138:141], v[222:225], v[40:43]
	v_mfma_f32_16x16x32_bf16 v[40:43], v[142:145], v[226:229], v[40:43]
	v_mfma_f32_16x16x32_bf16 v[28:31], v[130:133], v[230:233], v[28:31]
	v_mfma_f32_16x16x32_bf16 v[28:31], v[134:137], v[234:237], v[28:31]
	v_mfma_f32_16x16x32_bf16 v[24:27], v[138:141], v[230:233], v[24:27]
	v_mfma_f32_16x16x32_bf16 v[24:27], v[142:145], v[234:237], v[24:27]
	v_mfma_f32_16x16x32_bf16 v[12:15], v[130:133], v[238:241], v[12:15]
	v_mfma_f32_16x16x32_bf16 v[12:15], v[134:137], v[242:245], v[12:15]
	v_mfma_f32_16x16x32_bf16 v[8:11], v[138:141], v[238:241], v[8:11]
	v_mfma_f32_16x16x32_bf16 v[8:11], v[142:145], v[242:245], v[8:11]
	v_mfma_f32_16x16x32_bf16 v[52:55], v[188:191], v[214:217], v[52:55]
	v_mfma_f32_16x16x32_bf16 v[52:55], v[192:195], v[218:221], v[52:55]
	v_mfma_f32_16x16x32_bf16 v[48:51], v[196:199], v[214:217], v[48:51]
	v_mfma_f32_16x16x32_bf16 v[48:51], v[200:203], v[218:221], v[48:51]
	v_mfma_f32_16x16x32_bf16 v[36:39], v[188:191], v[222:225], v[36:39]
	v_mfma_f32_16x16x32_bf16 v[36:39], v[192:195], v[226:229], v[36:39]
	v_mfma_f32_16x16x32_bf16 v[32:35], v[196:199], v[222:225], v[32:35]
	v_mfma_f32_16x16x32_bf16 v[32:35], v[200:203], v[226:229], v[32:35]
	v_mfma_f32_16x16x32_bf16 v[20:23], v[188:191], v[230:233], v[20:23]
	v_mfma_f32_16x16x32_bf16 v[20:23], v[192:195], v[234:237], v[20:23]
	v_mfma_f32_16x16x32_bf16 v[16:19], v[196:199], v[230:233], v[16:19]
	v_mfma_f32_16x16x32_bf16 v[16:19], v[200:203], v[234:237], v[16:19]
	v_mfma_f32_16x16x32_bf16 v[4:7], v[188:191], v[238:241], v[4:7]
	v_mfma_f32_16x16x32_bf16 v[4:7], v[192:195], v[242:245], v[4:7]
	v_mfma_f32_16x16x32_bf16 v[0:3], v[196:199], v[238:241], v[0:3]
	v_mfma_f32_16x16x32_bf16 v[0:3], v[200:203], v[242:245], v[0:3]
	s_barrier
	s_add_i32 s63, s63, 2
	s_add_u32 s70, s70, 0x100
	s_addc_u32 s71, s71, 0
	s_add_u32 s10, s10, 0x100
	s_addc_u32 s61, s61, 0
	s_cmp_gt_u32 s63, 29
	s_cbranch_scc1 .LBB0_435

; #define PG8_STAGE(bufoff, gbase, voff) do { _Pragma("unroll") for (int _i = 0; _i < 2; ++_i) \
;         __builtin_amdgcn_global_load_lds((const unsigned*)((const char*)(gbase) + (voff)[_i]), (PG8_LAS unsigned*)(lds + (bufoff) + ldsw + _i * 8192), 16, 0, 0); } while (0)
; #define PG8_WAIT_V(n) asm volatile("s_waitcnt vmcnt(" #n ")" ::: "memory")
; #define PG8_WAIT_L(n) asm volatile("s_waitcnt lgkmcnt(" #n ")" ::: "memory")
; #define PG8_BAR __builtin_amdgcn_s_barrier()
; #define PG8_SCHED __builtin_amdgcn_sched_barrier(0)
;     ...
;             PG8_LDB(B0, 0, 0); PG8_LDB(B1, 0, 1); PG8_SCHED; PG8_LDA(At, 0, 0); PG8_STAGE(PG8_SA(1, 1), a1 + hstep, voffA);
;             PG8_WAIT_V(8); PG8_WAIT_L(0); PG8_BAR; PG8_MMA(0, 0, At, B0); PG8_MMA(0, 1, At, B1); PG8_BAR; PG8_SCHED;
;             PG8_LDA(At, 0, 1); PG8_STAGE(PG8_SB(0, 0), b2, voffB); PG8_STAGE(PG8_SB(0, 1), b2 + hstep, voffB); PG8_STAGE(PG8_SA(0, 0), a2, voffA);
.LBB0_666:
	v_add_u32_e32 v1, s70, v175
	s_add_u32 s33, s52, s54
	ds_read_b128 v[140:143], v1
	ds_read_b128 v[144:147], v1 offset:1024
	ds_read_b128 v[148:151], v1 offset:2048
	ds_read_b128 v[152:155], v1 offset:3072
	v_add_u32_e32 v1, s71, v175
	s_addc_u32 s58, s53, s55
	ds_read_b128 v[190:193], v1
	ds_read_b128 v[194:197], v1 offset:1024
	ds_read_b128 v[198:201], v1 offset:2048
	ds_read_b128 v[202:205], v1 offset:3072
	s_add_u32 s33, s33, 0x100
	s_addc_u32 s76, s58, 0
	s_and_b64 s[58:59], s[56:57], exec
	s_cselect_b32 s59, s34, s76
	s_cselect_b32 s58, s35, s33
	s_add_u32 s33, s73, s54
	s_addc_u32 s76, s74, s55
	s_and_b64 s[56:57], s[56:57], exec
	s_cselect_b32 s57, s45, s76
	s_cselect_b32 s56, s47, s33
	v_lshl_add_u64 v[2:3], v[136:137], 0, s[54:55]
	s_add_i32 m0, s63, 0xc000
	ds_read_b128 v[206:209], v179
	ds_read_b128 v[214:217], v179 offset:1024
	ds_read_b128 v[218:221], v179 offset:2048
	ds_read_b128 v[222:225], v179 offset:3072
	ds_read_b128 v[226:229], v179 offset:4096
	ds_read_b128 v[230:233], v179 offset:5120
	ds_read_b128 v[234:237], v179 offset:6144
	ds_read_b128 v[238:241], v179 offset:7168
	global_load_lds_dwordx4 v[2:3], off
	v_lshl_add_u64 v[2:3], v[138:139], 0, s[54:55]
	s_add_i32 m0, s63, 0xe000
	s_nop 0
	global_load_lds_dwordx4 v[2:3], off
	s_waitcnt vmcnt(8)
	s_waitcnt lgkmcnt(0)
	s_barrier
	v_mfma_f32_16x16x32_bf16 v[128:131], v[140:143], v[206:209], v[128:131]
	v_mfma_f32_16x16x32_bf16 v[128:131], v[144:147], v[214:217], v[128:131]
	v_mfma_f32_16x16x32_bf16 v[124:127], v[148:151], v[206:209], v[124:127]
	v_mfma_f32_16x16x32_bf16 v[124:127], v[152:155], v[214:217], v[124:127]
	v_mfma_f32_16x16x32_bf16 v[112:115], v[140:143], v[218:221], v[112:115]
	v_mfma_f32_16x16x32_bf16 v[112:115], v[144:147], v[222:225], v[112:115]
	v_mfma_f32_16x16x32_bf16 v[108:111], v[148:151], v[218:221], v[108:111]
	v_mfma_f32_16x16x32_bf16 v[108:111], v[152:155], v[222:225], v[108:111]
	v_mfma_f32_16x16x32_bf16 v[96:99], v[140:143], v[226:229], v[96:99]
	v_mfma_f32_16x16x32_bf16 v[96:99], v[144:147], v[230:233], v[96:99]
	v_mfma_f32_16x16x32_bf16 v[92:95], v[148:151], v[226:229], v[92:95]
	v_mfma_f32_16x16x32_bf16 v[92:95], v[152:155], v[230:233], v[92:95]
	v_mfma_f32_16x16x32_bf16 v[80:83], v[140:143], v[234:237], v[80:83]
	v_mfma_f32_16x16x32_bf16 v[80:83], v[144:147], v[238:241], v[80:83]
	v_mfma_f32_16x16x32_bf16 v[76:79], v[148:151], v[234:237], v[76:79]
	v_mfma_f32_16x16x32_bf16 v[76:79], v[152:155], v[238:241], v[76:79]
	v_mfma_f32_16x16x32_bf16 v[120:123], v[190:193], v[206:209], v[120:123]
	v_mfma_f32_16x16x32_bf16 v[120:123], v[194:197], v[214:217], v[120:123]
	v_mfma_f32_16x16x32_bf16 v[116:119], v[198:201], v[206:209], v[116:119]
	v_mfma_f32_16x16x32_bf16 v[116:119], v[202:205], v[214:217], v[116:119]
	v_mfma_f32_16x16x32_bf16 v[104:107], v[190:193], v[218:221], v[104:107]
	v_mfma_f32_16x16x32_bf16 v[104:107], v[194:197], v[222:225], v[104:107]
	v_mfma_f32_16x16x32_bf16 v[100:103], v[198:201], v[218:221], v[100:103]
	v_mfma_f32_16x16x32_bf16 v[100:103], v[202:205], v[222:225], v[100:103]
	v_mfma_f32_16x16x32_bf16 v[88:91], v[190:193], v[226:229], v[88:91]
	v_mfma_f32_16x16x32_bf16 v[88:91], v[194:197], v[230:233], v[88:91]
	v_mfma_f32_16x16x32_bf16 v[84:87], v[198:201], v[226:229], v[84:87]
	v_mfma_f32_16x16x32_bf16 v[84:87], v[202:205], v[230:233], v[84:87]
	v_mfma_f32_16x16x32_bf16 v[72:75], v[190:193], v[234:237], v[72:75]
	v_mfma_f32_16x16x32_bf16 v[72:75], v[194:197], v[238:241], v[72:75]
	v_mfma_f32_16x16x32_bf16 v[68:71], v[198:201], v[234:237], v[68:71]
	v_mfma_f32_16x16x32_bf16 v[68:71], v[202:205], v[238:241], v[68:71]
	s_barrier
	s_add_i32 s33, s70, s62
	v_lshl_add_u64 v[210:211], s[56:57], 0, v[158:159]
	s_mov_b32 m0, s33
	ds_read_b128 v[206:209], v179 offset:16384
	ds_read_b128 v[214:217], v179 offset:17408
	ds_read_b128 v[218:221], v179 offset:18432
	ds_read_b128 v[222:225], v179 offset:19456
	ds_read_b128 v[226:229], v179 offset:20480
	ds_read_b128 v[230:233], v179 offset:21504
	ds_read_b128 v[234:237], v179 offset:22528
	ds_read_b128 v[238:241], v179 offset:23552
	global_load_lds_dwordx4 v[210:211], off
	s_add_i32 m0, s33, 0x2000
	s_add_u32 s76, s56, 0x80000
	v_lshl_add_u64 v[242:243], s[56:57], 0, v[162:163]
	s_addc_u32 s77, s57, 0
	s_add_i32 s33, s71, s62
	global_load_lds_dwordx4 v[242:243], off
	v_lshl_add_u64 v[2:3], s[76:77], 0, v[158:159]
	s_mov_b32 m0, s33
	v_lshl_add_u64 v[244:245], s[58:59], 0, v[156:157]
	global_load_lds_dwordx4 v[2:3], off
	v_lshl_add_u64 v[2:3], s[76:77], 0, v[162:163]
	s_add_i32 m0, s33, 0x2000
	v_lshl_add_u64 v[246:247], s[58:59], 0, v[160:161]
	global_load_lds_dwordx4 v[2:3], off
	s_mov_b32 m0, s63
	s_nop 0
	global_load_lds_dwordx4 v[244:245], off
	s_mov_b32 m0, s64
	s_nop 0
	global_load_lds_dwordx4 v[246:247], off
	s_waitcnt vmcnt(8)
	s_waitcnt lgkmcnt(0)
	s_barrier
; #define PG8_STAGE(bufoff, gbase, voff) do { _Pragma("unroll") for (int _i = 0; _i < 2; ++_i) \
;         __builtin_amdgcn_global_load_lds((const unsigned*)((const char*)(gbase) + (voff)[_i]), (PG8_LAS unsigned*)(lds + (bufoff) + ldsw + _i * 8192), 16, 0, 0); } while (0)
; #define PG8_WAIT_V(n) asm volatile("s_waitcnt vmcnt(" #n ")" ::: "memory")
; #define PG8_WAIT_L(n) asm volatile("s_waitcnt lgkmcnt(" #n ")" ::: "memory")
; #define PG8_BAR __builtin_amdgcn_s_barrier()
; #define PG8_SCHED __builtin_amdgcn_sched_barrier(0)
;     ...
;             PG8_WAIT_V(8); PG8_WAIT_L(0); PG8_BAR; PG8_MMA(1, 0, At, B0); PG8_MMA(1, 1, At, B1); PG8_BAR; PG8_SCHED;
;             PG8_LDB(B0, 1, 0); PG8_LDB(B1, 1, 1); PG8_SCHED; PG8_LDA(At, 1, 0); PG8_STAGE(PG8_SA(0, 1), a2 + hstep, voffA);
;             PG8_WAIT_V(8); PG8_WAIT_L(0); PG8_BAR; PG8_MMA(0, 0, At, B0); PG8_MMA(0, 1, At, B1); PG8_BAR; PG8_SCHED;
	v_mfma_f32_16x16x32_bf16 v[64:67], v[140:143], v[206:209], v[64:67]
	v_mfma_f32_16x16x32_bf16 v[64:67], v[144:147], v[214:217], v[64:67]
	v_mfma_f32_16x16x32_bf16 v[60:63], v[148:151], v[206:209], v[60:63]
	v_mfma_f32_16x16x32_bf16 v[60:63], v[152:155], v[214:217], v[60:63]
	v_mfma_f32_16x16x32_bf16 v[48:51], v[140:143], v[218:221], v[48:51]
	v_mfma_f32_16x16x32_bf16 v[48:51], v[144:147], v[222:225], v[48:51]
	v_mfma_f32_16x16x32_bf16 v[44:47], v[148:151], v[218:221], v[44:47]
	v_mfma_f32_16x16x32_bf16 v[44:47], v[152:155], v[222:225], v[44:47]
	v_mfma_f32_16x16x32_bf16 v[32:35], v[140:143], v[226:229], v[32:35]
	v_mfma_f32_16x16x32_bf16 v[32:35], v[144:147], v[230:233], v[32:35]
	v_mfma_f32_16x16x32_bf16 v[28:31], v[148:151], v[226:229], v[28:31]
	v_mfma_f32_16x16x32_bf16 v[28:31], v[152:155], v[230:233], v[28:31]
	v_mfma_f32_16x16x32_bf16 v[16:19], v[140:143], v[234:237], v[16:19]
	v_mfma_f32_16x16x32_bf16 v[16:19], v[144:147], v[238:241], v[16:19]
	v_mfma_f32_16x16x32_bf16 v[12:15], v[148:151], v[234:237], v[12:15]
	v_mfma_f32_16x16x32_bf16 v[12:15], v[152:155], v[238:241], v[12:15]
	v_mfma_f32_16x16x32_bf16 v[56:59], v[190:193], v[206:209], v[56:59]
	v_mfma_f32_16x16x32_bf16 v[56:59], v[194:197], v[214:217], v[56:59]
	v_mfma_f32_16x16x32_bf16 v[52:55], v[198:201], v[206:209], v[52:55]
	v_mfma_f32_16x16x32_bf16 v[52:55], v[202:205], v[214:217], v[52:55]
	v_mfma_f32_16x16x32_bf16 v[40:43], v[190:193], v[218:221], v[40:43]
	v_mfma_f32_16x16x32_bf16 v[40:43], v[194:197], v[222:225], v[40:43]
	v_mfma_f32_16x16x32_bf16 v[36:39], v[198:201], v[218:221], v[36:39]
	v_mfma_f32_16x16x32_bf16 v[36:39], v[202:205], v[222:225], v[36:39]
	v_mfma_f32_16x16x32_bf16 v[24:27], v[190:193], v[226:229], v[24:27]
	v_mfma_f32_16x16x32_bf16 v[24:27], v[194:197], v[230:233], v[24:27]
	v_mfma_f32_16x16x32_bf16 v[20:23], v[198:201], v[226:229], v[20:23]
	v_mfma_f32_16x16x32_bf16 v[20:23], v[202:205], v[230:233], v[20:23]
	v_mfma_f32_16x16x32_bf16 v[8:11], v[190:193], v[234:237], v[8:11]
	v_mfma_f32_16x16x32_bf16 v[8:11], v[194:197], v[238:241], v[8:11]
	v_mfma_f32_16x16x32_bf16 v[2:5], v[198:201], v[234:237], v[4:7]
	v_mfma_f32_16x16x32_bf16 v[2:5], v[202:205], v[238:241], v[2:5]
	s_barrier
	s_add_i32 s33, 0, 0x18000
	v_add_u32_e32 v1, s33, v175
	s_add_i32 s76, 0, 0x1c000
	ds_read_b128 v[140:143], v1
	ds_read_b128 v[144:147], v1 offset:1024
	ds_read_b128 v[148:151], v1 offset:2048
	ds_read_b128 v[152:155], v1 offset:3072
	v_add_u32_e32 v1, s76, v175
	ds_read_b128 v[190:193], v1
	ds_read_b128 v[194:197], v1 offset:1024
	ds_read_b128 v[198:201], v1 offset:2048
	ds_read_b128 v[202:205], v1 offset:3072
	s_add_u32 s58, s58, 0x80000
	s_addc_u32 s59, s59, 0
	s_mov_b32 m0, s65
	v_lshl_add_u64 v[6:7], s[58:59], 0, v[156:157]
	ds_read_b128 v[206:209], v179 offset:32768
	ds_read_b128 v[214:217], v179 offset:33792
	ds_read_b128 v[218:221], v179 offset:34816
	ds_read_b128 v[222:225], v179 offset:35840
	ds_read_b128 v[226:229], v179 offset:36864
	ds_read_b128 v[230:233], v179 offset:37888
	ds_read_b128 v[234:237], v179 offset:38912
	ds_read_b128 v[238:241], v179 offset:39936
	global_load_lds_dwordx4 v[6:7], off
	v_lshl_add_u64 v[6:7], s[58:59], 0, v[160:161]
	s_mov_b32 m0, s66
	s_nop 0
	global_load_lds_dwordx4 v[6:7], off
	s_waitcnt vmcnt(8)
	s_waitcnt lgkmcnt(0)
	s_barrier
	v_mfma_f32_16x16x32_bf16 v[128:131], v[140:143], v[206:209], v[128:131]
	v_mfma_f32_16x16x32_bf16 v[128:131], v[144:147], v[214:217], v[128:131]
	v_mfma_f32_16x16x32_bf16 v[124:127], v[148:151], v[206:209], v[124:127]
	v_mfma_f32_16x16x32_bf16 v[124:127], v[152:155], v[214:217], v[124:127]
	v_mfma_f32_16x16x32_bf16 v[112:115], v[140:143], v[218:221], v[112:115]
	v_mfma_f32_16x16x32_bf16 v[112:115], v[144:147], v[222:225], v[112:115]
	v_mfma_f32_16x16x32_bf16 v[108:111], v[148:151], v[218:221], v[108:111]
	v_mfma_f32_16x16x32_bf16 v[108:111], v[152:155], v[222:225], v[108:111]
	v_mfma_f32_16x16x32_bf16 v[96:99], v[140:143], v[226:229], v[96:99]
	v_mfma_f32_16x16x32_bf16 v[96:99], v[144:147], v[230:233], v[96:99]
	v_mfma_f32_16x16x32_bf16 v[92:95], v[148:151], v[226:229], v[92:95]
	v_mfma_f32_16x16x32_bf16 v[92:95], v[152:155], v[230:233], v[92:95]
	v_mfma_f32_16x16x32_bf16 v[80:83], v[140:143], v[234:237], v[80:83]
	v_mfma_f32_16x16x32_bf16 v[80:83], v[144:147], v[238:241], v[80:83]
	v_mfma_f32_16x16x32_bf16 v[76:79], v[148:151], v[234:237], v[76:79]
	v_mfma_f32_16x16x32_bf16 v[76:79], v[152:155], v[238:241], v[76:79]
	v_mfma_f32_16x16x32_bf16 v[120:123], v[190:193], v[206:209], v[120:123]
	v_mfma_f32_16x16x32_bf16 v[120:123], v[194:197], v[214:217], v[120:123]
	v_mfma_f32_16x16x32_bf16 v[116:119], v[198:201], v[206:209], v[116:119]
	v_mfma_f32_16x16x32_bf16 v[116:119], v[202:205], v[214:217], v[116:119]
	v_mfma_f32_16x16x32_bf16 v[104:107], v[190:193], v[218:221], v[104:107]
	v_mfma_f32_16x16x32_bf16 v[104:107], v[194:197], v[222:225], v[104:107]
	v_mfma_f32_16x16x32_bf16 v[100:103], v[198:201], v[218:221], v[100:103]
	v_mfma_f32_16x16x32_bf16 v[100:103], v[202:205], v[222:225], v[100:103]
	v_mfma_f32_16x16x32_bf16 v[88:91], v[190:193], v[226:229], v[88:91]
	v_mfma_f32_16x16x32_bf16 v[88:91], v[194:197], v[230:233], v[88:91]
	v_mfma_f32_16x16x32_bf16 v[84:87], v[198:201], v[226:229], v[84:87]
	v_mfma_f32_16x16x32_bf16 v[84:87], v[202:205], v[230:233], v[84:87]
	v_mfma_f32_16x16x32_bf16 v[72:75], v[190:193], v[234:237], v[72:75]
	v_mfma_f32_16x16x32_bf16 v[72:75], v[194:197], v[238:241], v[72:75]
	v_mfma_f32_16x16x32_bf16 v[68:71], v[198:201], v[234:237], v[68:71]
	v_mfma_f32_16x16x32_bf16 v[68:71], v[202:205], v[238:241], v[68:71]
	s_barrier
; #define PG8_STAGE(bufoff, gbase, voff) do { _Pragma("unroll") for (int _i = 0; _i < 2; ++_i) \
;         __builtin_amdgcn_global_load_lds((const unsigned*)((const char*)(gbase) + (voff)[_i]), (PG8_LAS unsigned*)(lds + (bufoff) + ldsw + _i * 8192), 16, 0, 0); } while (0)
; #define PG8_WAIT_V(n) asm volatile("s_waitcnt vmcnt(" #n ")" ::: "memory")
; #define PG8_WAIT_L(n) asm volatile("s_waitcnt lgkmcnt(" #n ")" ::: "memory")
; #define PG8_BAR __builtin_amdgcn_s_barrier()
; #define PG8_SCHED __builtin_amdgcn_sched_barrier(0)
;     ...
;             PG8_LDA(At, 1, 1); PG8_STAGE(PG8_SB(1, 0), b3, voffB); PG8_STAGE(PG8_SB(1, 1), b3 + hstep, voffB); PG8_STAGE(PG8_SA(1, 0), a3, voffA);
;             PG8_WAIT_V(8); PG8_WAIT_L(0); PG8_BAR; PG8_MMA(1, 0, At, B0); PG8_MMA(1, 1, At, B1); PG8_BAR; PG8_SCHED;
	s_add_i32 s33, s33, s62
	v_lshl_add_u64 v[6:7], v[210:211], 0, s[40:41]
	s_mov_b32 m0, s33
	ds_read_b128 v[206:209], v179 offset:49152
	ds_read_b128 v[214:217], v179 offset:50176
	ds_read_b128 v[218:221], v179 offset:51200
	ds_read_b128 v[222:225], v179 offset:52224
	ds_read_b128 v[226:229], v179 offset:53248
	ds_read_b128 v[230:233], v179 offset:54272
	ds_read_b128 v[234:237], v179 offset:55296
	ds_read_b128 v[238:241], v179 offset:56320
	global_load_lds_dwordx4 v[6:7], off
	s_add_i32 m0, s33, 0x2000
	s_add_u32 s56, s56, 0x80080
	v_lshl_add_u64 v[6:7], v[242:243], 0, s[40:41]
	s_addc_u32 s57, s57, 0
	s_add_i32 s33, s76, s62
	global_load_lds_dwordx4 v[6:7], off
	v_lshl_add_u64 v[6:7], s[56:57], 0, v[158:159]
	s_mov_b32 m0, s33
	s_nop 0
	global_load_lds_dwordx4 v[6:7], off
	v_lshl_add_u64 v[6:7], s[56:57], 0, v[162:163]
	s_add_i32 m0, s33, 0x2000
	s_nop 0
	global_load_lds_dwordx4 v[6:7], off
	v_lshl_add_u64 v[6:7], v[244:245], 0, s[40:41]
	s_mov_b32 m0, s68
	s_nop 0
	global_load_lds_dwordx4 v[6:7], off
	v_lshl_add_u64 v[6:7], v[246:247], 0, s[40:41]
	s_mov_b32 m0, s69
	s_nop 0
	global_load_lds_dwordx4 v[6:7], off
	s_waitcnt vmcnt(8)
	s_waitcnt lgkmcnt(0)
	s_barrier
	v_mfma_f32_16x16x32_bf16 v[64:67], v[140:143], v[206:209], v[64:67]
	v_mfma_f32_16x16x32_bf16 v[64:67], v[144:147], v[214:217], v[64:67]
	v_mfma_f32_16x16x32_bf16 v[60:63], v[148:151], v[206:209], v[60:63]
	v_mfma_f32_16x16x32_bf16 v[60:63], v[152:155], v[214:217], v[60:63]
	v_mfma_f32_16x16x32_bf16 v[48:51], v[140:143], v[218:221], v[48:51]
	v_mfma_f32_16x16x32_bf16 v[48:51], v[144:147], v[222:225], v[48:51]
	v_mfma_f32_16x16x32_bf16 v[44:47], v[148:151], v[218:221], v[44:47]
	v_mfma_f32_16x16x32_bf16 v[44:47], v[152:155], v[222:225], v[44:47]
	v_mfma_f32_16x16x32_bf16 v[32:35], v[140:143], v[226:229], v[32:35]
	v_mfma_f32_16x16x32_bf16 v[32:35], v[144:147], v[230:233], v[32:35]
	v_mfma_f32_16x16x32_bf16 v[28:31], v[148:151], v[226:229], v[28:31]
	v_mfma_f32_16x16x32_bf16 v[28:31], v[152:155], v[230:233], v[28:31]
	v_mfma_f32_16x16x32_bf16 v[16:19], v[140:143], v[234:237], v[16:19]
	v_mfma_f32_16x16x32_bf16 v[16:19], v[144:147], v[238:241], v[16:19]
	v_mfma_f32_16x16x32_bf16 v[12:15], v[148:151], v[234:237], v[12:15]
	v_mfma_f32_16x16x32_bf16 v[12:15], v[152:155], v[238:241], v[12:15]
	v_mfma_f32_16x16x32_bf16 v[56:59], v[190:193], v[206:209], v[56:59]
	v_mfma_f32_16x16x32_bf16 v[52:55], v[198:201], v[206:209], v[52:55]
	v_mfma_f32_16x16x32_bf16 v[40:43], v[190:193], v[218:221], v[40:43]
	v_mfma_f32_16x16x32_bf16 v[36:39], v[198:201], v[218:221], v[36:39]
	v_mfma_f32_16x16x32_bf16 v[24:27], v[190:193], v[226:229], v[24:27]
	v_mfma_f32_16x16x32_bf16 v[20:23], v[198:201], v[226:229], v[20:23]
	v_mfma_f32_16x16x32_bf16 v[6:9], v[190:193], v[234:237], v[8:11]
	v_mfma_f32_16x16x32_bf16 v[2:5], v[198:201], v[234:237], v[2:5]
	v_mfma_f32_16x16x32_bf16 v[56:59], v[194:197], v[214:217], v[56:59]
	v_mfma_f32_16x16x32_bf16 v[52:55], v[202:205], v[214:217], v[52:55]
	v_mfma_f32_16x16x32_bf16 v[40:43], v[194:197], v[222:225], v[40:43]
	v_mfma_f32_16x16x32_bf16 v[36:39], v[202:205], v[222:225], v[36:39]
	v_mfma_f32_16x16x32_bf16 v[24:27], v[194:197], v[230:233], v[24:27]
	v_mfma_f32_16x16x32_bf16 v[20:23], v[202:205], v[230:233], v[20:23]
	v_mfma_f32_16x16x32_bf16 v[8:11], v[194:197], v[238:241], v[6:9]
	v_mfma_f32_16x16x32_bf16 v[4:7], v[202:205], v[238:241], v[2:5]
	s_barrier
	s_add_i32 s75, s75, 2
	s_add_u32 s54, s54, 0x100
	s_addc_u32 s55, s55, 0
	s_cmp_gt_u32 s75, 29
	s_cbranch_scc1 .LBB0_671

; #define PG8_STAGE(bufoff, gbase, voff) do { _Pragma("unroll") for (int _i = 0; _i < 2; ++_i) \
;         __builtin_amdgcn_global_load_lds((const unsigned*)((const char*)(gbase) + (voff)[_i]), (PG8_LAS unsigned*)(lds + (bufoff) + ldsw + _i * 8192), 16, 0, 0); } while (0)
; #define PG8_WAIT_V(n) asm volatile("s_waitcnt vmcnt(" #n ")" ::: "memory")
; #define PG8_WAIT_L(n) asm volatile("s_waitcnt lgkmcnt(" #n ")" ::: "memory")
; #define PG8_BAR __builtin_amdgcn_s_barrier()
; #define PG8_SCHED __builtin_amdgcn_sched_barrier(0)
;     ...
;             PG8_LDB(B0, 0, 0); PG8_LDB(B1, 0, 1); PG8_SCHED; PG8_LDA(At, 0, 0); PG8_STAGE(PG8_SA(1, 1), a1 + hstep, voffA);
;             PG8_WAIT_V(8); PG8_WAIT_L(0); PG8_BAR; PG8_MMA(0, 0, At, B0); PG8_MMA(0, 1, At, B1); PG8_BAR; PG8_SCHED;
;             PG8_LDA(At, 0, 1); PG8_STAGE(PG8_SB(0, 0), b2, voffB); PG8_STAGE(PG8_SB(0, 1), b2 + hstep, voffB); PG8_STAGE(PG8_SA(0, 0), a2, voffA);
.LBB0_851:
	v_add_u32_e32 v157, s60, v149
	ds_read_b128 v[166:169], v157
	ds_read_b128 v[170:173], v157 offset:1024
	ds_read_b128 v[174:177], v157 offset:2048
	ds_read_b128 v[178:181], v157 offset:3072
	v_add_u32_e32 v157, s61, v149
	ds_read_b128 v[182:185], v157
	ds_read_b128 v[186:189], v157 offset:1024
	ds_read_b128 v[190:193], v157 offset:2048
	ds_read_b128 v[194:197], v157 offset:3072
	s_add_u32 s33, s42, 0xfffc0080
	s_addc_u32 s46, s43, -1
	s_and_b64 s[44:45], s[44:45], exec
	s_cselect_b32 s47, s34, s46
	s_cselect_b32 s46, s35, s33
	s_cselect_b32 s45, s25, s66
	s_cselect_b32 s44, s37, s65
	v_lshl_add_u64 v[210:211], s[42:43], 0, v[138:139]
	s_add_i32 m0, s51, 0xc000
	ds_read_b128 v[198:201], v153
	ds_read_b128 v[202:205], v153 offset:1024
	ds_read_b128 v[206:209], v153 offset:2048
	ds_read_b128 v[214:217], v153 offset:3072
	ds_read_b128 v[218:221], v153 offset:4096
	ds_read_b128 v[222:225], v153 offset:5120
	ds_read_b128 v[226:229], v153 offset:6144
	ds_read_b128 v[230:233], v153 offset:7168
	global_load_lds_dwordx4 v[210:211], off
	v_lshl_add_u64 v[210:211], s[42:43], 0, v[140:141]
	s_add_i32 m0, s51, 0xe000
	s_nop 0
	global_load_lds_dwordx4 v[210:211], off
	s_waitcnt vmcnt(8)
	s_waitcnt lgkmcnt(0)
	s_barrier
	v_mfma_i32_16x16x64_i8 v[124:127], v[166:169], v[198:201], v[124:127]
	v_mfma_i32_16x16x64_i8 v[124:127], v[170:173], v[202:205], v[124:127]
	v_mfma_i32_16x16x64_i8 v[120:123], v[174:177], v[198:201], v[120:123]
	v_mfma_i32_16x16x64_i8 v[120:123], v[178:181], v[202:205], v[120:123]
	v_mfma_i32_16x16x64_i8 v[108:111], v[166:169], v[206:209], v[108:111]
	v_mfma_i32_16x16x64_i8 v[108:111], v[170:173], v[214:217], v[108:111]
	v_mfma_i32_16x16x64_i8 v[100:103], v[174:177], v[206:209], v[100:103]
	v_mfma_i32_16x16x64_i8 v[100:103], v[178:181], v[214:217], v[100:103]
	v_mfma_i32_16x16x64_i8 v[92:95], v[166:169], v[218:221], v[92:95]
	v_mfma_i32_16x16x64_i8 v[92:95], v[170:173], v[222:225], v[92:95]
	v_mfma_i32_16x16x64_i8 v[84:87], v[174:177], v[218:221], v[84:87]
	v_mfma_i32_16x16x64_i8 v[84:87], v[178:181], v[222:225], v[84:87]
	v_mfma_i32_16x16x64_i8 v[76:79], v[166:169], v[226:229], v[76:79]
	v_mfma_i32_16x16x64_i8 v[76:79], v[170:173], v[230:233], v[76:79]
	v_mfma_i32_16x16x64_i8 v[68:71], v[174:177], v[226:229], v[68:71]
	v_mfma_i32_16x16x64_i8 v[68:71], v[178:181], v[230:233], v[68:71]
	v_mfma_i32_16x16x64_i8 v[116:119], v[182:185], v[198:201], v[116:119]
	v_mfma_i32_16x16x64_i8 v[116:119], v[186:189], v[202:205], v[116:119]
	v_mfma_i32_16x16x64_i8 v[112:115], v[190:193], v[198:201], v[112:115]
	v_mfma_i32_16x16x64_i8 v[112:115], v[194:197], v[202:205], v[112:115]
	v_mfma_i32_16x16x64_i8 v[104:107], v[182:185], v[206:209], v[104:107]
	v_mfma_i32_16x16x64_i8 v[104:107], v[186:189], v[214:217], v[104:107]
	v_mfma_i32_16x16x64_i8 v[96:99], v[190:193], v[206:209], v[96:99]
	v_mfma_i32_16x16x64_i8 v[96:99], v[194:197], v[214:217], v[96:99]
	v_mfma_i32_16x16x64_i8 v[88:91], v[182:185], v[218:221], v[88:91]
	v_mfma_i32_16x16x64_i8 v[88:91], v[186:189], v[222:225], v[88:91]
	v_mfma_i32_16x16x64_i8 v[80:83], v[190:193], v[218:221], v[80:83]
	v_mfma_i32_16x16x64_i8 v[80:83], v[194:197], v[222:225], v[80:83]
	v_mfma_i32_16x16x64_i8 v[72:75], v[182:185], v[226:229], v[72:75]
	v_mfma_i32_16x16x64_i8 v[72:75], v[186:189], v[230:233], v[72:75]
	v_mfma_i32_16x16x64_i8 v[64:67], v[190:193], v[226:229], v[64:67]
	v_mfma_i32_16x16x64_i8 v[64:67], v[194:197], v[230:233], v[64:67]
	s_barrier
	s_add_i32 s33, s60, s48
	v_lshl_add_u64 v[210:211], s[44:45], 0, v[132:133]
	s_mov_b32 m0, s33
	ds_read_b128 v[198:201], v153 offset:16384
	ds_read_b128 v[202:205], v153 offset:17408
	ds_read_b128 v[206:209], v153 offset:18432
	ds_read_b128 v[214:217], v153 offset:19456
	ds_read_b128 v[218:221], v153 offset:20480
	ds_read_b128 v[222:225], v153 offset:21504
	ds_read_b128 v[226:229], v153 offset:22528
	ds_read_b128 v[230:233], v153 offset:23552
	global_load_lds_dwordx4 v[210:211], off
	s_add_i32 m0, s33, 0x2000
	s_add_u32 s68, s44, 0x40000
	v_lshl_add_u64 v[234:235], s[44:45], 0, v[128:129]
	s_addc_u32 s69, s45, 0
	s_add_i32 s33, s61, s48
	global_load_lds_dwordx4 v[234:235], off
	v_lshl_add_u64 v[236:237], s[68:69], 0, v[132:133]
	s_mov_b32 m0, s33
	v_lshl_add_u64 v[238:239], s[46:47], 0, v[130:131]
	global_load_lds_dwordx4 v[236:237], off
	v_lshl_add_u64 v[236:237], s[68:69], 0, v[128:129]
	s_add_i32 m0, s33, 0x2000
	s_nop 0
	global_load_lds_dwordx4 v[236:237], off
	v_lshl_add_u64 v[236:237], s[46:47], 0, v[134:135]
	s_mov_b32 m0, s51
	s_nop 0
	global_load_lds_dwordx4 v[236:237], off
	s_mov_b32 m0, s52
	s_nop 0
	global_load_lds_dwordx4 v[238:239], off
	s_waitcnt vmcnt(8)
	s_waitcnt lgkmcnt(0)
	s_barrier
; #define PG8_STAGE(bufoff, gbase, voff) do { _Pragma("unroll") for (int _i = 0; _i < 2; ++_i) \
;         __builtin_amdgcn_global_load_lds((const unsigned*)((const char*)(gbase) + (voff)[_i]), (PG8_LAS unsigned*)(lds + (bufoff) + ldsw + _i * 8192), 16, 0, 0); } while (0)
; #define PG8_WAIT_V(n) asm volatile("s_waitcnt vmcnt(" #n ")" ::: "memory")
; #define PG8_WAIT_L(n) asm volatile("s_waitcnt lgkmcnt(" #n ")" ::: "memory")
; #define PG8_BAR __builtin_amdgcn_s_barrier()
; #define PG8_SCHED __builtin_amdgcn_sched_barrier(0)
;     ...
;             PG8_WAIT_V(8); PG8_WAIT_L(0); PG8_BAR; PG8_MMA(1, 0, At, B0); PG8_MMA(1, 1, At, B1); PG8_BAR; PG8_SCHED;
;             PG8_LDB(B0, 1, 0); PG8_LDB(B1, 1, 1); PG8_SCHED; PG8_LDA(At, 1, 0); PG8_STAGE(PG8_SA(0, 1), a2 + hstep, voffA);
;             PG8_WAIT_V(8); PG8_WAIT_L(0); PG8_BAR; PG8_MMA(0, 0, At, B0); PG8_MMA(0, 1, At, B1); PG8_BAR; PG8_SCHED;
	v_mfma_i32_16x16x64_i8 v[60:63], v[166:169], v[198:201], v[60:63]
	v_mfma_i32_16x16x64_i8 v[60:63], v[170:173], v[202:205], v[60:63]
	v_mfma_i32_16x16x64_i8 v[52:55], v[174:177], v[198:201], v[52:55]
	v_mfma_i32_16x16x64_i8 v[52:55], v[178:181], v[202:205], v[52:55]
	v_mfma_i32_16x16x64_i8 v[44:47], v[166:169], v[206:209], v[44:47]
	v_mfma_i32_16x16x64_i8 v[44:47], v[170:173], v[214:217], v[44:47]
	v_mfma_i32_16x16x64_i8 v[36:39], v[174:177], v[206:209], v[36:39]
	v_mfma_i32_16x16x64_i8 v[36:39], v[178:181], v[214:217], v[36:39]
	v_mfma_i32_16x16x64_i8 v[28:31], v[166:169], v[218:221], v[28:31]
	v_mfma_i32_16x16x64_i8 v[28:31], v[170:173], v[222:225], v[28:31]
	v_mfma_i32_16x16x64_i8 v[20:23], v[174:177], v[218:221], v[20:23]
	v_mfma_i32_16x16x64_i8 v[20:23], v[178:181], v[222:225], v[20:23]
	v_mfma_i32_16x16x64_i8 v[12:15], v[166:169], v[226:229], v[12:15]
	v_mfma_i32_16x16x64_i8 v[12:15], v[170:173], v[230:233], v[12:15]
	v_mfma_i32_16x16x64_i8 v[4:7], v[174:177], v[226:229], v[4:7]
	v_mfma_i32_16x16x64_i8 v[4:7], v[178:181], v[230:233], v[4:7]
	v_mfma_i32_16x16x64_i8 v[56:59], v[182:185], v[198:201], v[56:59]
	v_mfma_i32_16x16x64_i8 v[56:59], v[186:189], v[202:205], v[56:59]
	v_mfma_i32_16x16x64_i8 v[48:51], v[190:193], v[198:201], v[48:51]
	v_mfma_i32_16x16x64_i8 v[48:51], v[194:197], v[202:205], v[48:51]
	v_mfma_i32_16x16x64_i8 v[40:43], v[182:185], v[206:209], v[40:43]
	v_mfma_i32_16x16x64_i8 v[40:43], v[186:189], v[214:217], v[40:43]
	v_mfma_i32_16x16x64_i8 v[32:35], v[190:193], v[206:209], v[32:35]
	v_mfma_i32_16x16x64_i8 v[32:35], v[194:197], v[214:217], v[32:35]
	v_mfma_i32_16x16x64_i8 v[24:27], v[182:185], v[218:221], v[24:27]
	v_mfma_i32_16x16x64_i8 v[24:27], v[186:189], v[222:225], v[24:27]
	v_mfma_i32_16x16x64_i8 v[16:19], v[190:193], v[218:221], v[16:19]
	v_mfma_i32_16x16x64_i8 v[16:19], v[194:197], v[222:225], v[16:19]
	v_mfma_i32_16x16x64_i8 v[8:11], v[182:185], v[226:229], v[8:11]
	v_mfma_i32_16x16x64_i8 v[8:11], v[186:189], v[230:233], v[8:11]
	v_mfma_i32_16x16x64_i8 v[0:3], v[190:193], v[226:229], v[0:3]
	v_mfma_i32_16x16x64_i8 v[0:3], v[194:197], v[230:233], v[0:3]
	s_barrier
	s_add_i32 s33, 0, 0x18000
	v_add_u32_e32 v157, s33, v149
	s_add_i32 s68, 0, 0x1c000
	ds_read_b128 v[166:169], v157
	ds_read_b128 v[170:173], v157 offset:1024
	ds_read_b128 v[174:177], v157 offset:2048
	ds_read_b128 v[178:181], v157 offset:3072
	v_add_u32_e32 v157, s68, v149
	ds_read_b128 v[182:185], v157
	ds_read_b128 v[186:189], v157 offset:1024
	ds_read_b128 v[190:193], v157 offset:2048
	ds_read_b128 v[194:197], v157 offset:3072
	s_add_u32 s46, s46, 0x40000
	s_addc_u32 s47, s47, 0
	s_mov_b32 m0, s53
	v_lshl_add_u64 v[240:241], s[46:47], 0, v[134:135]
	ds_read_b128 v[198:201], v153 offset:32768
	ds_read_b128 v[202:205], v153 offset:33792
	ds_read_b128 v[206:209], v153 offset:34816
	ds_read_b128 v[214:217], v153 offset:35840
	ds_read_b128 v[218:221], v153 offset:36864
	ds_read_b128 v[222:225], v153 offset:37888
	ds_read_b128 v[226:229], v153 offset:38912
	ds_read_b128 v[230:233], v153 offset:39936
	global_load_lds_dwordx4 v[240:241], off
	v_lshl_add_u64 v[240:241], s[46:47], 0, v[130:131]
	s_mov_b32 m0, s54
	s_nop 0
	global_load_lds_dwordx4 v[240:241], off
	s_waitcnt vmcnt(8)
	s_waitcnt lgkmcnt(0)
	s_barrier
	v_mfma_i32_16x16x64_i8 v[124:127], v[166:169], v[198:201], v[124:127]
	v_mfma_i32_16x16x64_i8 v[124:127], v[170:173], v[202:205], v[124:127]
	v_mfma_i32_16x16x64_i8 v[120:123], v[174:177], v[198:201], v[120:123]
	v_mfma_i32_16x16x64_i8 v[120:123], v[178:181], v[202:205], v[120:123]
	v_mfma_i32_16x16x64_i8 v[108:111], v[166:169], v[206:209], v[108:111]
	v_mfma_i32_16x16x64_i8 v[108:111], v[170:173], v[214:217], v[108:111]
	v_mfma_i32_16x16x64_i8 v[100:103], v[174:177], v[206:209], v[100:103]
	v_mfma_i32_16x16x64_i8 v[100:103], v[178:181], v[214:217], v[100:103]
	v_mfma_i32_16x16x64_i8 v[92:95], v[166:169], v[218:221], v[92:95]
	v_mfma_i32_16x16x64_i8 v[92:95], v[170:173], v[222:225], v[92:95]
	v_mfma_i32_16x16x64_i8 v[84:87], v[174:177], v[218:221], v[84:87]
	v_mfma_i32_16x16x64_i8 v[84:87], v[178:181], v[222:225], v[84:87]
	v_mfma_i32_16x16x64_i8 v[76:79], v[166:169], v[226:229], v[76:79]
	v_mfma_i32_16x16x64_i8 v[76:79], v[170:173], v[230:233], v[76:79]
	v_mfma_i32_16x16x64_i8 v[68:71], v[174:177], v[226:229], v[68:71]
	v_mfma_i32_16x16x64_i8 v[68:71], v[178:181], v[230:233], v[68:71]
	v_mfma_i32_16x16x64_i8 v[116:119], v[182:185], v[198:201], v[116:119]
	v_mfma_i32_16x16x64_i8 v[116:119], v[186:189], v[202:205], v[116:119]
	v_mfma_i32_16x16x64_i8 v[112:115], v[190:193], v[198:201], v[112:115]
	v_mfma_i32_16x16x64_i8 v[112:115], v[194:197], v[202:205], v[112:115]
	v_mfma_i32_16x16x64_i8 v[104:107], v[182:185], v[206:209], v[104:107]
	v_mfma_i32_16x16x64_i8 v[104:107], v[186:189], v[214:217], v[104:107]
	v_mfma_i32_16x16x64_i8 v[96:99], v[190:193], v[206:209], v[96:99]
	v_mfma_i32_16x16x64_i8 v[96:99], v[194:197], v[214:217], v[96:99]
	v_mfma_i32_16x16x64_i8 v[88:91], v[182:185], v[218:221], v[88:91]
	v_mfma_i32_16x16x64_i8 v[88:91], v[186:189], v[222:225], v[88:91]
	v_mfma_i32_16x16x64_i8 v[80:83], v[190:193], v[218:221], v[80:83]
	v_mfma_i32_16x16x64_i8 v[80:83], v[194:197], v[222:225], v[80:83]
	v_mfma_i32_16x16x64_i8 v[72:75], v[182:185], v[226:229], v[72:75]
	v_mfma_i32_16x16x64_i8 v[72:75], v[186:189], v[230:233], v[72:75]
	v_mfma_i32_16x16x64_i8 v[64:67], v[190:193], v[226:229], v[64:67]
	v_mfma_i32_16x16x64_i8 v[64:67], v[194:197], v[230:233], v[64:67]
	s_barrier
; #define PG8_STAGE(bufoff, gbase, voff) do { _Pragma("unroll") for (int _i = 0; _i < 2; ++_i) \
;         __builtin_amdgcn_global_load_lds((const unsigned*)((const char*)(gbase) + (voff)[_i]), (PG8_LAS unsigned*)(lds + (bufoff) + ldsw + _i * 8192), 16, 0, 0); } while (0)
; #define PG8_WAIT_V(n) asm volatile("s_waitcnt vmcnt(" #n ")" ::: "memory")
; #define PG8_WAIT_L(n) asm volatile("s_waitcnt lgkmcnt(" #n ")" ::: "memory")
; #define PG8_BAR __builtin_amdgcn_s_barrier()
; #define PG8_SCHED __builtin_amdgcn_sched_barrier(0)
;     ...
;         for (int t = 0; t < nt; t += 2) {
;     ...
;             PG8_LDA(At, 1, 1); PG8_STAGE(PG8_SB(1, 0), b3, voffB); PG8_STAGE(PG8_SB(1, 1), b3 + hstep, voffB); PG8_STAGE(PG8_SA(1, 0), a3, voffA);
;             PG8_WAIT_V(8); PG8_WAIT_L(0); PG8_BAR; PG8_MMA(1, 0, At, B0); PG8_MMA(1, 1, At, B1); PG8_BAR; PG8_SCHED;
	s_add_i32 s33, s33, s48
	v_lshl_add_u64 v[210:211], v[210:211], 0, s[10:11]
	s_mov_b32 m0, s33
	ds_read_b128 v[198:201], v153 offset:49152
	ds_read_b128 v[202:205], v153 offset:50176
	ds_read_b128 v[206:209], v153 offset:51200
	ds_read_b128 v[214:217], v153 offset:52224
	ds_read_b128 v[218:221], v153 offset:53248
	ds_read_b128 v[222:225], v153 offset:54272
	ds_read_b128 v[226:229], v153 offset:55296
	ds_read_b128 v[230:233], v153 offset:56320
	global_load_lds_dwordx4 v[210:211], off
	s_add_i32 m0, s33, 0x2000
	s_add_u32 s44, s44, 0x40080
	v_lshl_add_u64 v[210:211], v[234:235], 0, s[10:11]
	s_addc_u32 s45, s45, 0
	s_add_i32 s33, s68, s48
	global_load_lds_dwordx4 v[210:211], off
	v_lshl_add_u64 v[210:211], s[44:45], 0, v[132:133]
	s_mov_b32 m0, s33
	s_nop 0
	global_load_lds_dwordx4 v[210:211], off
	v_lshl_add_u64 v[210:211], s[44:45], 0, v[128:129]
	s_add_i32 m0, s33, 0x2000
	s_nop 0
	global_load_lds_dwordx4 v[210:211], off
	v_lshl_add_u64 v[210:211], v[236:237], 0, s[10:11]
	s_mov_b32 m0, s56
	s_nop 0
	global_load_lds_dwordx4 v[210:211], off
	v_lshl_add_u64 v[210:211], v[238:239], 0, s[10:11]
	s_mov_b32 m0, s57
	s_nop 0
	global_load_lds_dwordx4 v[210:211], off
	s_waitcnt vmcnt(8)
	s_waitcnt lgkmcnt(0)
	s_barrier
	v_mfma_i32_16x16x64_i8 v[60:63], v[166:169], v[198:201], v[60:63]
	v_mfma_i32_16x16x64_i8 v[60:63], v[170:173], v[202:205], v[60:63]
	v_mfma_i32_16x16x64_i8 v[52:55], v[174:177], v[198:201], v[52:55]
	v_mfma_i32_16x16x64_i8 v[52:55], v[178:181], v[202:205], v[52:55]
	v_mfma_i32_16x16x64_i8 v[44:47], v[166:169], v[206:209], v[44:47]
	v_mfma_i32_16x16x64_i8 v[44:47], v[170:173], v[214:217], v[44:47]
	v_mfma_i32_16x16x64_i8 v[36:39], v[174:177], v[206:209], v[36:39]
	v_mfma_i32_16x16x64_i8 v[36:39], v[178:181], v[214:217], v[36:39]
	v_mfma_i32_16x16x64_i8 v[28:31], v[166:169], v[218:221], v[28:31]
	v_mfma_i32_16x16x64_i8 v[28:31], v[170:173], v[222:225], v[28:31]
	v_mfma_i32_16x16x64_i8 v[20:23], v[174:177], v[218:221], v[20:23]
	v_mfma_i32_16x16x64_i8 v[20:23], v[178:181], v[222:225], v[20:23]
	v_mfma_i32_16x16x64_i8 v[12:15], v[166:169], v[226:229], v[12:15]
	v_mfma_i32_16x16x64_i8 v[12:15], v[170:173], v[230:233], v[12:15]
	v_mfma_i32_16x16x64_i8 v[4:7], v[174:177], v[226:229], v[4:7]
	v_mfma_i32_16x16x64_i8 v[4:7], v[178:181], v[230:233], v[4:7]
	v_mfma_i32_16x16x64_i8 v[56:59], v[182:185], v[198:201], v[56:59]
	v_mfma_i32_16x16x64_i8 v[56:59], v[186:189], v[202:205], v[56:59]
	v_mfma_i32_16x16x64_i8 v[48:51], v[190:193], v[198:201], v[48:51]
	v_mfma_i32_16x16x64_i8 v[48:51], v[194:197], v[202:205], v[48:51]
	v_mfma_i32_16x16x64_i8 v[40:43], v[182:185], v[206:209], v[40:43]
	v_mfma_i32_16x16x64_i8 v[40:43], v[186:189], v[214:217], v[40:43]
	v_mfma_i32_16x16x64_i8 v[32:35], v[190:193], v[206:209], v[32:35]
	v_mfma_i32_16x16x64_i8 v[32:35], v[194:197], v[214:217], v[32:35]
	v_mfma_i32_16x16x64_i8 v[24:27], v[182:185], v[218:221], v[24:27]
	v_mfma_i32_16x16x64_i8 v[24:27], v[186:189], v[222:225], v[24:27]
	v_mfma_i32_16x16x64_i8 v[16:19], v[190:193], v[218:221], v[16:19]
	v_mfma_i32_16x16x64_i8 v[16:19], v[194:197], v[222:225], v[16:19]
	v_mfma_i32_16x16x64_i8 v[8:11], v[182:185], v[226:229], v[8:11]
	v_mfma_i32_16x16x64_i8 v[8:11], v[186:189], v[230:233], v[8:11]
	v_mfma_i32_16x16x64_i8 v[0:3], v[190:193], v[226:229], v[0:3]
	v_mfma_i32_16x16x64_i8 v[0:3], v[194:197], v[230:233], v[0:3]
	s_barrier
	s_add_i32 s67, s67, 2
	s_add_u32 s42, s42, 0x100
	s_addc_u32 s43, s43, 0
	s_add_u32 s65, s65, 0x100
	s_addc_u32 s66, s66, 0
	s_cmp_gt_u32 s67, 13
	s_cbranch_scc1 .LBB0_854

; #define PG8_STAGE(bufoff, gbase, voff) do { _Pragma("unroll") for (int _i = 0; _i < 2; ++_i) \
;         __builtin_amdgcn_global_load_lds((const unsigned*)((const char*)(gbase) + (voff)[_i]), (PG8_LAS unsigned*)(lds + (bufoff) + ldsw + _i * 8192), 16, 0, 0); } while (0)
; #define PG8_WAIT_V(n) asm volatile("s_waitcnt vmcnt(" #n ")" ::: "memory")
; #define PG8_WAIT_L(n) asm volatile("s_waitcnt lgkmcnt(" #n ")" ::: "memory")
; #define PG8_BAR __builtin_amdgcn_s_barrier()
; #define PG8_SCHED __builtin_amdgcn_sched_barrier(0)
;     ...
;             PG8_LDB(B0, 0, 0); PG8_LDB(B1, 0, 1); PG8_SCHED; PG8_LDA(At, 0, 0); PG8_STAGE(PG8_SA(1, 1), a1 + hstep, voffA);
;             PG8_WAIT_V(8); PG8_WAIT_L(0); PG8_BAR; PG8_MMA(0, 0, At, B0); PG8_MMA(0, 1, At, B1); PG8_BAR; PG8_SCHED;
;             PG8_LDA(At, 0, 1); PG8_STAGE(PG8_SB(0, 0), b2, voffB); PG8_STAGE(PG8_SB(0, 1), b2 + hstep, voffB); PG8_STAGE(PG8_SA(0, 0), a2, voffA);
;             PG8_WAIT_V(8); PG8_WAIT_L(0); PG8_BAR; PG8_MMA(1, 0, At, B0); PG8_MMA(1, 1, At, B1); PG8_BAR; PG8_SCHED;
.LBB0_936:
	ds_read_b128 v[16:19], v187
	ds_read_b128 v[20:23], v187 offset:16
	ds_read_b128 v[24:27], v187 offset:2048
	ds_read_b128 v[28:31], v187 offset:2064
	ds_read_b128 v[0:3], v188
	ds_read_b128 v[4:7], v188 offset:16
	ds_read_b128 v[8:11], v188 offset:2048
	ds_read_b128 v[12:15], v188 offset:2064
	s_add_u32 s24, s20, 0xfff50080
	s_addc_u32 s25, s21, -1
	s_cmp_eq_u32 s48, 40
	s_cselect_b32 s29, s5, s25
	s_cselect_b32 s28, s4, s24
	s_cselect_b32 s25, s19, s47
	s_cselect_b32 s24, s18, s46
	v_lshl_add_u64 v[214:215], s[20:21], 0, v[168:169]
	s_add_i32 m0, s31, 0xc000
	ds_read_b128 v[176:179], v189
	ds_read_b128 v[180:183], v189 offset:16
	ds_read_b128 v[190:193], v189 offset:2048
	ds_read_b128 v[194:197], v189 offset:2064
	ds_read_b128 v[198:201], v189 offset:4096
	ds_read_b128 v[202:205], v189 offset:4112
	ds_read_b128 v[206:209], v189 offset:6144
	ds_read_b128 v[210:213], v189 offset:6160
	global_load_lds_dwordx4 v[214:215], off
	v_lshl_add_u64 v[214:215], s[20:21], 0, v[170:171]
	s_add_i32 m0, s31, 0xe000
	s_nop 0
	global_load_lds_dwordx4 v[214:215], off
	s_waitcnt vmcnt(8)
	s_waitcnt lgkmcnt(0)
	s_barrier
	v_mfma_f32_16x16x128_f8f6f4 v[156:159], v[16:23], v[176:183], v[156:159]
	v_mfma_f32_16x16x128_f8f6f4 v[152:155], v[24:31], v[176:183], v[152:155]
	v_mfma_f32_16x16x128_f8f6f4 v[148:151], v[16:23], v[190:197], v[148:151]
	v_mfma_f32_16x16x128_f8f6f4 v[144:147], v[24:31], v[190:197], v[144:147]
	v_mfma_f32_16x16x128_f8f6f4 v[128:131], v[16:23], v[198:205], v[128:131]
	v_mfma_f32_16x16x128_f8f6f4 v[120:123], v[24:31], v[198:205], v[120:123]
	v_mfma_f32_16x16x128_f8f6f4 v[112:115], v[16:23], v[206:213], v[112:115]
	v_mfma_f32_16x16x128_f8f6f4 v[104:107], v[24:31], v[206:213], v[104:107]
	v_mfma_f32_16x16x128_f8f6f4 v[140:143], v[0:7], v[176:183], v[140:143]
	v_mfma_f32_16x16x128_f8f6f4 v[136:139], v[8:15], v[176:183], v[136:139]
	v_mfma_f32_16x16x128_f8f6f4 v[132:135], v[0:7], v[190:197], v[132:135]
	v_mfma_f32_16x16x128_f8f6f4 v[124:127], v[8:15], v[190:197], v[124:127]
	v_mfma_f32_16x16x128_f8f6f4 v[116:119], v[0:7], v[198:205], v[116:119]
	v_mfma_f32_16x16x128_f8f6f4 v[108:111], v[8:15], v[198:205], v[108:111]
	v_mfma_f32_16x16x128_f8f6f4 v[100:103], v[0:7], v[206:213], v[100:103]
	v_mfma_f32_16x16x128_f8f6f4 v[96:99], v[8:15], v[206:213], v[96:99]
	s_barrier
	s_add_i32 s49, s40, s30
	v_lshl_add_u64 v[176:177], s[24:25], 0, v[162:163]
	s_mov_b32 m0, s49
	ds_read_b128 v[190:193], v189 offset:16384
	ds_read_b128 v[194:197], v189 offset:16400
	ds_read_b128 v[198:201], v189 offset:18432
	ds_read_b128 v[202:205], v189 offset:18448
	ds_read_b128 v[206:209], v189 offset:20480
	ds_read_b128 v[210:213], v189 offset:20496
	ds_read_b128 v[214:217], v189 offset:22528
	ds_read_b128 v[218:221], v189 offset:22544
	global_load_lds_dwordx4 v[176:177], off
	s_add_i32 m0, s49, 0x2000
	s_add_u32 s50, s24, 0xb0000
	v_lshl_add_u64 v[178:179], s[24:25], 0, v[166:167]
	s_addc_u32 s51, s25, 0
	s_add_i32 s49, s41, s30
	global_load_lds_dwordx4 v[178:179], off
	v_lshl_add_u64 v[180:181], s[50:51], 0, v[162:163]
	s_mov_b32 m0, s49
	v_lshl_add_u64 v[182:183], s[28:29], 0, v[164:165]
	global_load_lds_dwordx4 v[180:181], off
	v_lshl_add_u64 v[180:181], s[50:51], 0, v[166:167]
	s_add_i32 m0, s49, 0x2000
	s_nop 0
	global_load_lds_dwordx4 v[180:181], off
	v_lshl_add_u64 v[180:181], s[28:29], 0, v[160:161]
	s_mov_b32 m0, s31
	s_nop 0
	global_load_lds_dwordx4 v[180:181], off
	s_mov_b32 m0, s33
	s_nop 0
	global_load_lds_dwordx4 v[182:183], off
	s_waitcnt vmcnt(8)
	s_waitcnt lgkmcnt(0)
	s_barrier
	v_mfma_f32_16x16x128_f8f6f4 v[92:95], v[16:23], v[190:197], v[92:95]
	v_mfma_f32_16x16x128_f8f6f4 v[88:91], v[24:31], v[190:197], v[88:91]
	v_mfma_f32_16x16x128_f8f6f4 v[80:83], v[16:23], v[198:205], v[80:83]
	v_mfma_f32_16x16x128_f8f6f4 v[72:75], v[24:31], v[198:205], v[72:75]
	v_mfma_f32_16x16x128_f8f6f4 v[64:67], v[16:23], v[206:213], v[64:67]
	v_mfma_f32_16x16x128_f8f6f4 v[56:59], v[24:31], v[206:213], v[56:59]
	v_mfma_f32_16x16x128_f8f6f4 v[48:51], v[16:23], v[214:221], v[48:51]
	v_mfma_f32_16x16x128_f8f6f4 v[40:43], v[24:31], v[214:221], v[40:43]
	v_mfma_f32_16x16x128_f8f6f4 v[84:87], v[0:7], v[190:197], v[84:87]
	v_mfma_f32_16x16x128_f8f6f4 v[76:79], v[8:15], v[190:197], v[76:79]
	v_mfma_f32_16x16x128_f8f6f4 v[68:71], v[0:7], v[198:205], v[68:71]
	v_mfma_f32_16x16x128_f8f6f4 v[60:63], v[8:15], v[198:205], v[60:63]
	v_mfma_f32_16x16x128_f8f6f4 v[52:55], v[0:7], v[206:213], v[52:55]
	v_mfma_f32_16x16x128_f8f6f4 v[44:47], v[8:15], v[206:213], v[44:47]
	v_mfma_f32_16x16x128_f8f6f4 v[36:39], v[0:7], v[214:221], v[36:39]
	v_mfma_f32_16x16x128_f8f6f4 v[32:35], v[8:15], v[214:221], v[32:35]
	s_barrier
; #define PG8_STAGE(bufoff, gbase, voff) do { _Pragma("unroll") for (int _i = 0; _i < 2; ++_i) \
;         __builtin_amdgcn_global_load_lds((const unsigned*)((const char*)(gbase) + (voff)[_i]), (PG8_LAS unsigned*)(lds + (bufoff) + ldsw + _i * 8192), 16, 0, 0); } while (0)
; #define PG8_WAIT_V(n) asm volatile("s_waitcnt vmcnt(" #n ")" ::: "memory")
; #define PG8_WAIT_L(n) asm volatile("s_waitcnt lgkmcnt(" #n ")" ::: "memory")
; #define PG8_BAR __builtin_amdgcn_s_barrier()
; #define PG8_SCHED __builtin_amdgcn_sched_barrier(0)
;     ...
;             PG8_LDB(B0, 1, 0); PG8_LDB(B1, 1, 1); PG8_SCHED; PG8_LDA(At, 1, 0); PG8_STAGE(PG8_SA(0, 1), a2 + hstep, voffA);
;             PG8_WAIT_V(8); PG8_WAIT_L(0); PG8_BAR; PG8_MMA(0, 0, At, B0); PG8_MMA(0, 1, At, B1); PG8_BAR; PG8_SCHED;
;             PG8_LDA(At, 1, 1); PG8_STAGE(PG8_SB(1, 0), b3, voffB); PG8_STAGE(PG8_SB(1, 1), b3 + hstep, voffB); PG8_STAGE(PG8_SA(1, 0), a3, voffA);
;             PG8_WAIT_V(8); PG8_WAIT_L(0); PG8_BAR; PG8_MMA(1, 0, At, B0); PG8_MMA(1, 1, At, B1); PG8_BAR; PG8_SCHED;
;     ...
;         if constexpr (F8) asm volatile("s_nop 15\n\ts_nop 15" ::: "memory");
;         if constexpr (ALIGN_EPI) { if (wr == 0) PG8_BAR; }
	s_add_i32 s49, 0, 0x18000
	s_add_i32 s50, 0, 0x1c000
	v_add_u32_e32 v12, s49, v185
	v_add_u32_e32 v28, s50, v185
	ds_read_b128 v[0:3], v12
	ds_read_b128 v[4:7], v12 offset:16
	ds_read_b128 v[8:11], v12 offset:2048
	ds_read_b128 v[12:15], v12 offset:2064
	ds_read_b128 v[16:19], v28
	ds_read_b128 v[20:23], v28 offset:16
	ds_read_b128 v[24:27], v28 offset:2048
	ds_read_b128 v[28:31], v28 offset:2064
	s_add_u32 s28, s28, 0xb0000
	s_addc_u32 s29, s29, 0
	s_mov_b32 m0, s34
	v_lshl_add_u64 v[222:223], s[28:29], 0, v[160:161]
	ds_read_b128 v[190:193], v189 offset:32768
	ds_read_b128 v[194:197], v189 offset:32784
	ds_read_b128 v[198:201], v189 offset:34816
	ds_read_b128 v[202:205], v189 offset:34832
	ds_read_b128 v[206:209], v189 offset:36864
	ds_read_b128 v[210:213], v189 offset:36880
	ds_read_b128 v[214:217], v189 offset:38912
	ds_read_b128 v[218:221], v189 offset:38928
	global_load_lds_dwordx4 v[222:223], off
	v_lshl_add_u64 v[222:223], s[28:29], 0, v[164:165]
	s_mov_b32 m0, s35
	s_nop 0
	global_load_lds_dwordx4 v[222:223], off
	s_waitcnt vmcnt(8)
	s_waitcnt lgkmcnt(0)
	s_barrier
	v_mfma_f32_16x16x128_f8f6f4 v[156:159], v[0:7], v[190:197], v[156:159]
	v_mfma_f32_16x16x128_f8f6f4 v[152:155], v[8:15], v[190:197], v[152:155]
	v_mfma_f32_16x16x128_f8f6f4 v[148:151], v[0:7], v[198:205], v[148:151]
	v_mfma_f32_16x16x128_f8f6f4 v[144:147], v[8:15], v[198:205], v[144:147]
	v_mfma_f32_16x16x128_f8f6f4 v[128:131], v[0:7], v[206:213], v[128:131]
	v_mfma_f32_16x16x128_f8f6f4 v[120:123], v[8:15], v[206:213], v[120:123]
	v_mfma_f32_16x16x128_f8f6f4 v[112:115], v[0:7], v[214:221], v[112:115]
	v_mfma_f32_16x16x128_f8f6f4 v[104:107], v[8:15], v[214:221], v[104:107]
	v_mfma_f32_16x16x128_f8f6f4 v[140:143], v[16:23], v[190:197], v[140:143]
	v_mfma_f32_16x16x128_f8f6f4 v[136:139], v[24:31], v[190:197], v[136:139]
	v_mfma_f32_16x16x128_f8f6f4 v[132:135], v[16:23], v[198:205], v[132:135]
	v_mfma_f32_16x16x128_f8f6f4 v[124:127], v[24:31], v[198:205], v[124:127]
	v_mfma_f32_16x16x128_f8f6f4 v[116:119], v[16:23], v[206:213], v[116:119]
	v_mfma_f32_16x16x128_f8f6f4 v[108:111], v[24:31], v[206:213], v[108:111]
	v_mfma_f32_16x16x128_f8f6f4 v[100:103], v[16:23], v[214:221], v[100:103]
	v_mfma_f32_16x16x128_f8f6f4 v[96:99], v[24:31], v[214:221], v[96:99]
	s_barrier
	s_add_i32 s28, s49, s30
	v_lshl_add_u64 v[176:177], v[176:177], 0, s[8:9]
	s_mov_b32 m0, s28
	ds_read_b128 v[190:193], v189 offset:49152
	ds_read_b128 v[194:197], v189 offset:49168
	ds_read_b128 v[198:201], v189 offset:51200
	ds_read_b128 v[202:205], v189 offset:51216
	ds_read_b128 v[206:209], v189 offset:53248
	ds_read_b128 v[210:213], v189 offset:53264
	ds_read_b128 v[214:217], v189 offset:55296
	ds_read_b128 v[218:221], v189 offset:55312
	global_load_lds_dwordx4 v[176:177], off
	s_add_i32 m0, s28, 0x2000
	s_add_u32 s24, s24, 0xb0080
	v_lshl_add_u64 v[176:177], v[178:179], 0, s[8:9]
	s_addc_u32 s25, s25, 0
	s_add_i32 s28, s50, s30
	global_load_lds_dwordx4 v[176:177], off
	v_lshl_add_u64 v[176:177], s[24:25], 0, v[162:163]
	s_mov_b32 m0, s28
	s_nop 0
	global_load_lds_dwordx4 v[176:177], off
	v_lshl_add_u64 v[176:177], s[24:25], 0, v[166:167]
	s_add_i32 m0, s28, 0x2000
	s_nop 0
	global_load_lds_dwordx4 v[176:177], off
	v_lshl_add_u64 v[176:177], v[180:181], 0, s[8:9]
	s_mov_b32 m0, s37
	s_nop 0
	global_load_lds_dwordx4 v[176:177], off
	v_lshl_add_u64 v[176:177], v[182:183], 0, s[8:9]
	s_mov_b32 m0, s38
	s_nop 0
	global_load_lds_dwordx4 v[176:177], off
	s_waitcnt vmcnt(8)
	s_waitcnt lgkmcnt(0)
	s_barrier
	v_mfma_f32_16x16x128_f8f6f4 v[92:95], v[0:7], v[190:197], v[92:95]
	v_mfma_f32_16x16x128_f8f6f4 v[88:91], v[8:15], v[190:197], v[88:91]
	v_mfma_f32_16x16x128_f8f6f4 v[80:83], v[0:7], v[198:205], v[80:83]
	v_mfma_f32_16x16x128_f8f6f4 v[72:75], v[8:15], v[198:205], v[72:75]
	v_mfma_f32_16x16x128_f8f6f4 v[64:67], v[0:7], v[206:213], v[64:67]
	v_mfma_f32_16x16x128_f8f6f4 v[56:59], v[8:15], v[206:213], v[56:59]
	v_mfma_f32_16x16x128_f8f6f4 v[48:51], v[0:7], v[214:221], v[48:51]
	v_mfma_f32_16x16x128_f8f6f4 v[40:43], v[8:15], v[214:221], v[40:43]
	v_mfma_f32_16x16x128_f8f6f4 v[84:87], v[16:23], v[190:197], v[84:87]
	v_mfma_f32_16x16x128_f8f6f4 v[76:79], v[24:31], v[190:197], v[76:79]
	v_mfma_f32_16x16x128_f8f6f4 v[68:71], v[16:23], v[198:205], v[68:71]
	v_mfma_f32_16x16x128_f8f6f4 v[60:63], v[24:31], v[198:205], v[60:63]
	v_mfma_f32_16x16x128_f8f6f4 v[52:55], v[16:23], v[206:213], v[52:55]
	v_mfma_f32_16x16x128_f8f6f4 v[44:47], v[24:31], v[206:213], v[44:47]
	v_mfma_f32_16x16x128_f8f6f4 v[36:39], v[16:23], v[214:221], v[36:39]
	v_mfma_f32_16x16x128_f8f6f4 v[32:35], v[24:31], v[214:221], v[32:35]
	s_barrier
	s_add_i32 s48, s48, 2
	s_add_u32 s20, s20, 0x100
	s_addc_u32 s21, s21, 0
	s_add_u32 s46, s46, 0x100
	s_addc_u32 s47, s47, 0
	s_cmp_gt_u32 s48, 41
	s_cbranch_scc0 .LBB0_936
	s_nop 15
	s_nop 15
	s_and_b64 vcc, exec, s[10:11]
	s_cbranch_vccz .LBB0_939
	s_barrier
